# S5 scan: LDS input reads software-pipelined one step ahead (second register set)
# speedup vs baseline: 1.0095x; 1.0027x over previous
; #define LAS __attribute__((address_space(3)))
; __device__ __forceinline__ unsigned f2bf(float f) { unsigned u = __builtin_bit_cast(unsigned, f); return (u + 0x7fffu + ((u >> 16) & 1u)) >> 16; }
; __device__ __forceinline__ void s5_phase(LAS unsigned char* lds, const unsigned char* ws, const bf16_t* proj, const float* c_re, const float* c_im, const float* dskip, bf16_t* z,
;                                          int vcu, int G, int wave, int lane) {
;     ...
;             if (lane < 32) {
;                 LAS f32x4* up4 = (LAS f32x4*)(Uc + lane * 16);
;                 up4[0] = (f32x4){bflo(ua.x), bfhi(ua.x), bflo(ua.y), bfhi(ua.y)}; up4[1] = (f32x4){bflo(ua.z), bfhi(ua.z), bflo(ua.w), bfhi(ua.w)};
;                 up4[2] = (f32x4){bflo(ub.x), bfhi(ub.x), bflo(ub.y), bfhi(ub.y)}; up4[3] = (f32x4){bflo(ub.z), bfhi(ub.z), bflo(ub.w), bfhi(ub.w)};
;             }
; #pragma unroll
;             for (int k = 0; k < 32; ++k) {
;                 f32x2 xa = (f32x2){0.f, 0.f}, xb = (f32x2){0.f, 0.f};
; #pragma unroll
;                 for (int q = 0; q < 4; ++q) { const f32x4 u4 = *(const LAS f32x4*)(Uc + k * 16 + 4 * q);
;                     xa = __builtin_elementwise_fma((f32x2){u4[0], u4[0]}, (f32x2){bbre[4 * q], bbim[4 * q]}, xa);
;                     xb = __builtin_elementwise_fma((f32x2){u4[1], u4[1]}, (f32x2){bbre[4 * q + 1], bbim[4 * q + 1]}, xb);
;                     xa = __builtin_elementwise_fma((f32x2){u4[2], u4[2]}, (f32x2){bbre[4 * q + 2], bbim[4 * q + 2]}, xa);
;                     xb = __builtin_elementwise_fma((f32x2){u4[3], u4[3]}, (f32x2){bbre[4 * q + 3], bbim[4 * q + 3]}, xb); }
;                 const f32x2 xx = xa + xb;
;                 const float nr = are * hre - aim * him + xx[0], ni = are * him + aim * hre + xx[1]; hre = nr; him = ni;
;                 Hc[k * 136 + n] = (bf16_t)f2bf(hre); Hc[k * 136 + 64 + n] = (bf16_t)f2bf(him);
;             }
.LBB0_386:
	s_or_b64 exec, exec, s[0:1]
	s_waitcnt vmcnt(19)
	v_mov_b32_e32 v40, s14
	s_waitcnt vmcnt(18)
	ds_read_b128 v[200:203], v40
	ds_read_b128 v[204:207], v40 offset:16
	ds_read_b128 v[208:211], v40 offset:32
	ds_read_b128 v[212:215], v40 offset:48
	ds_read_b128 v[42:45], v40 offset:64
	ds_read_b128 v[122:125], v40 offset:80
	ds_read_b128 v[126:129], v40 offset:96
	ds_read_b128 v[130:133], v40 offset:112
	s_waitcnt vmcnt(13)
	v_lshlrev_b32_e32 v108, 16, v108
	s_waitcnt lgkmcnt(7)
	v_pk_fma_f32 v[46:47], v[200:201], v[64:65], 0 op_sel_hi:[0,1,0]
	v_pk_fma_f32 v[200:201], v[200:201], v[12:13], 0 op_sel:[1,0,0] op_sel_hi:[1,1,0]
	v_pk_fma_f32 v[46:47], v[202:203], v[66:67], v[46:47] op_sel_hi:[0,1,1]
	v_mov_b32_e32 v202, v203
	v_pk_fma_f32 v[200:201], v[202:203], v[14:15], v[200:201] op_sel_hi:[0,1,1]
	s_waitcnt lgkmcnt(6)
	v_pk_fma_f32 v[202:203], v[204:205], v[68:69], v[46:47] op_sel_hi:[0,1,1]
	v_pk_fma_f32 v[200:201], v[204:205], v[8:9], v[200:201] op_sel:[1,0,0]
	v_mov_b32_e32 v46, v207
	v_pk_fma_f32 v[202:203], v[206:207], v[70:71], v[202:203] op_sel_hi:[0,1,1]
	v_pk_fma_f32 v[200:201], v[46:47], v[10:11], v[200:201] op_sel_hi:[0,1,1]
	s_waitcnt lgkmcnt(5)
	v_pk_fma_f32 v[202:203], v[208:209], v[72:73], v[202:203] op_sel_hi:[0,1,1]
	v_pk_fma_f32 v[200:201], v[208:209], v[4:5], v[200:201] op_sel:[1,0,0]
	v_mov_b32_e32 v46, v211
	v_pk_fma_f32 v[202:203], v[210:211], v[74:75], v[202:203] op_sel_hi:[0,1,1]
	v_pk_fma_f32 v[200:201], v[46:47], v[6:7], v[200:201] op_sel_hi:[0,1,1]
	s_waitcnt lgkmcnt(4)
	v_pk_fma_f32 v[202:203], v[212:213], v[76:77], v[202:203] op_sel_hi:[0,1,1]
	v_pk_fma_f32 v[200:201], v[212:213], v[0:1], v[200:201] op_sel:[1,0,0]
	v_mov_b32_e32 v46, v215
	v_pk_fma_f32 v[202:203], v[214:215], v[78:79], v[202:203] op_sel_hi:[0,1,1]
	v_pk_fma_f32 v[200:201], v[46:47], v[2:3], v[200:201] op_sel_hi:[0,1,1]
	v_pk_add_f32 v[200:201], v[200:201], v[202:203]
	v_mul_f32_e32 v202, v61, v87
	v_pk_fma_f32 v[202:203], v[60:61], v[86:87], v[202:203] op_sel_hi:[1,1,0] neg_lo:[0,0,1] neg_hi:[0,0,1]
	s_nop 0
	v_pk_add_f32 v[46:47], v[202:203], v[200:201]
	v_mov_b32_e32 v202, v87
	v_pk_mul_f32 v[202:203], v[60:61], v[202:203]
	v_bfe_u32 v41, v46, 16, 1
	v_pk_fma_f32 v[202:203], v[50:51], v[86:87], v[202:203]
	v_add3_u32 v41, v46, v41, s29
	v_pk_add_f32 v[86:87], v[202:203], v[200:201] op_sel:[0,1] op_sel_hi:[1,0]
	ds_write_b16_d16_hi v88, v41
	v_bfe_u32 v41, v86, 16, 1
	v_add3_u32 v41, v86, v41, s29
	ds_write_b16_d16_hi v88, v41 offset:128
	ds_read_b128 v[200:203], v40 offset:128
	ds_read_b128 v[204:207], v40 offset:144
	ds_read_b128 v[208:211], v40 offset:160
	ds_read_b128 v[212:215], v40 offset:176
	s_waitcnt lgkmcnt(9)
	v_pk_fma_f32 v[134:135], v[42:43], v[64:65], 0 op_sel_hi:[0,1,0]
	v_pk_fma_f32 v[42:43], v[42:43], v[12:13], 0 op_sel:[1,0,0] op_sel_hi:[1,1,0]
	v_pk_fma_f32 v[134:135], v[44:45], v[66:67], v[134:135] op_sel_hi:[0,1,1]
	v_mov_b32_e32 v44, v45
	v_pk_fma_f32 v[42:43], v[44:45], v[14:15], v[42:43] op_sel_hi:[0,1,1]
	s_waitcnt lgkmcnt(8)
	v_pk_fma_f32 v[44:45], v[122:123], v[68:69], v[134:135] op_sel_hi:[0,1,1]
	v_pk_fma_f32 v[42:43], v[122:123], v[8:9], v[42:43] op_sel:[1,0,0]
	v_mov_b32_e32 v122, v125
	v_pk_fma_f32 v[44:45], v[124:125], v[70:71], v[44:45] op_sel_hi:[0,1,1]
	v_pk_fma_f32 v[42:43], v[122:123], v[10:11], v[42:43] op_sel_hi:[0,1,1]
	s_waitcnt lgkmcnt(7)
	v_pk_fma_f32 v[44:45], v[126:127], v[72:73], v[44:45] op_sel_hi:[0,1,1]
	v_pk_fma_f32 v[42:43], v[126:127], v[4:5], v[42:43] op_sel:[1,0,0]
	v_mov_b32_e32 v122, v129
	v_pk_fma_f32 v[44:45], v[128:129], v[74:75], v[44:45] op_sel_hi:[0,1,1]
	v_pk_fma_f32 v[42:43], v[122:123], v[6:7], v[42:43] op_sel_hi:[0,1,1]
	s_waitcnt lgkmcnt(6)
	v_pk_fma_f32 v[44:45], v[130:131], v[76:77], v[44:45] op_sel_hi:[0,1,1]
	v_pk_fma_f32 v[42:43], v[130:131], v[0:1], v[42:43] op_sel:[1,0,0]
	v_mov_b32_e32 v122, v133
	v_pk_fma_f32 v[44:45], v[132:133], v[78:79], v[44:45] op_sel_hi:[0,1,1]
	v_pk_fma_f32 v[42:43], v[122:123], v[2:3], v[42:43] op_sel_hi:[0,1,1]
	v_pk_add_f32 v[42:43], v[42:43], v[44:45]
	v_pk_mul_f32 v[44:45], v[50:51], v[86:87]
	s_nop 0
	v_pk_fma_f32 v[44:45], v[60:61], v[46:47], v[44:45] neg_lo:[0,0,1] neg_hi:[0,0,1]
	s_nop 0
	v_pk_add_f32 v[134:135], v[44:45], v[42:43]
	v_pk_mul_f32 v[44:45], v[50:51], v[46:47]
	v_bfe_u32 v41, v134, 16, 1
	v_pk_fma_f32 v[44:45], v[60:61], v[86:87], v[44:45]
	v_add3_u32 v41, v134, v41, s29
	v_pk_add_f32 v[46:47], v[44:45], v[42:43] op_sel:[0,1] op_sel_hi:[1,0]
	ds_write_b16_d16_hi v88, v41 offset:272
	v_bfe_u32 v41, v46, 16, 1
	v_add3_u32 v41, v46, v41, s29
	ds_write_b16_d16_hi v88, v41 offset:400
	ds_read_b128 v[42:45], v40 offset:192
	ds_read_b128 v[122:125], v40 offset:208
	ds_read_b128 v[126:129], v40 offset:224
	ds_read_b128 v[130:133], v40 offset:240
	s_waitcnt lgkmcnt(9)
	v_pk_fma_f32 v[86:87], v[200:201], v[64:65], 0 op_sel_hi:[0,1,0]
	v_pk_fma_f32 v[200:201], v[200:201], v[12:13], 0 op_sel:[1,0,0] op_sel_hi:[1,1,0]
	v_pk_fma_f32 v[86:87], v[202:203], v[66:67], v[86:87] op_sel_hi:[0,1,1]
	v_mov_b32_e32 v202, v203
	v_pk_fma_f32 v[200:201], v[202:203], v[14:15], v[200:201] op_sel_hi:[0,1,1]
	s_waitcnt lgkmcnt(8)
	v_pk_fma_f32 v[202:203], v[204:205], v[68:69], v[86:87] op_sel_hi:[0,1,1]
	v_pk_fma_f32 v[200:201], v[204:205], v[8:9], v[200:201] op_sel:[1,0,0]
	v_mov_b32_e32 v86, v207
	v_pk_fma_f32 v[202:203], v[206:207], v[70:71], v[202:203] op_sel_hi:[0,1,1]
	v_pk_fma_f32 v[200:201], v[86:87], v[10:11], v[200:201] op_sel_hi:[0,1,1]
	s_waitcnt lgkmcnt(7)
; #define LAS __attribute__((address_space(3)))
; __device__ __forceinline__ unsigned f2bf(float f) { unsigned u = __builtin_bit_cast(unsigned, f); return (u + 0x7fffu + ((u >> 16) & 1u)) >> 16; }
; __device__ __forceinline__ void s5_phase(LAS unsigned char* lds, const unsigned char* ws, const bf16_t* proj, const float* c_re, const float* c_im, const float* dskip, bf16_t* z,
;                                          int vcu, int G, int wave, int lane) {
;     ...
;             for (int k = 0; k < 32; ++k) {
;                 f32x2 xa = (f32x2){0.f, 0.f}, xb = (f32x2){0.f, 0.f};
; #pragma unroll
;                 for (int q = 0; q < 4; ++q) { const f32x4 u4 = *(const LAS f32x4*)(Uc + k * 16 + 4 * q);
;                     xa = __builtin_elementwise_fma((f32x2){u4[0], u4[0]}, (f32x2){bbre[4 * q], bbim[4 * q]}, xa);
;                     xb = __builtin_elementwise_fma((f32x2){u4[1], u4[1]}, (f32x2){bbre[4 * q + 1], bbim[4 * q + 1]}, xb);
;                     xa = __builtin_elementwise_fma((f32x2){u4[2], u4[2]}, (f32x2){bbre[4 * q + 2], bbim[4 * q + 2]}, xa);
;                     xb = __builtin_elementwise_fma((f32x2){u4[3], u4[3]}, (f32x2){bbre[4 * q + 3], bbim[4 * q + 3]}, xb); }
;                 const f32x2 xx = xa + xb;
;                 const float nr = are * hre - aim * him + xx[0], ni = are * him + aim * hre + xx[1]; hre = nr; him = ni;
;                 Hc[k * 136 + n] = (bf16_t)f2bf(hre); Hc[k * 136 + 64 + n] = (bf16_t)f2bf(him);
;             }
	v_pk_fma_f32 v[202:203], v[208:209], v[72:73], v[202:203] op_sel_hi:[0,1,1]
	v_pk_fma_f32 v[200:201], v[208:209], v[4:5], v[200:201] op_sel:[1,0,0]
	v_mov_b32_e32 v86, v211
	v_pk_fma_f32 v[202:203], v[210:211], v[74:75], v[202:203] op_sel_hi:[0,1,1]
	v_pk_fma_f32 v[200:201], v[86:87], v[6:7], v[200:201] op_sel_hi:[0,1,1]
	s_waitcnt lgkmcnt(6)
	v_pk_fma_f32 v[202:203], v[212:213], v[76:77], v[202:203] op_sel_hi:[0,1,1]
	v_pk_fma_f32 v[200:201], v[212:213], v[0:1], v[200:201] op_sel:[1,0,0]
	v_mov_b32_e32 v86, v215
	v_pk_fma_f32 v[202:203], v[214:215], v[78:79], v[202:203] op_sel_hi:[0,1,1]
	v_pk_fma_f32 v[200:201], v[86:87], v[2:3], v[200:201] op_sel_hi:[0,1,1]
	v_pk_add_f32 v[200:201], v[200:201], v[202:203]
	v_pk_mul_f32 v[202:203], v[50:51], v[46:47]
	s_nop 0
	v_pk_fma_f32 v[202:203], v[60:61], v[134:135], v[202:203] neg_lo:[0,0,1] neg_hi:[0,0,1]
	s_nop 0
	v_pk_add_f32 v[86:87], v[202:203], v[200:201]
	v_pk_mul_f32 v[202:203], v[50:51], v[134:135]
	v_bfe_u32 v41, v86, 16, 1
	v_pk_fma_f32 v[202:203], v[60:61], v[46:47], v[202:203]
	v_add3_u32 v41, v86, v41, s29
	v_pk_add_f32 v[46:47], v[202:203], v[200:201] op_sel:[0,1] op_sel_hi:[1,0]
	ds_write_b16_d16_hi v88, v41 offset:544
	v_bfe_u32 v41, v46, 16, 1
	v_add3_u32 v41, v46, v41, s29
	ds_write_b16_d16_hi v88, v41 offset:672
	ds_read_b128 v[200:203], v40 offset:256
	ds_read_b128 v[204:207], v40 offset:272
	ds_read_b128 v[208:211], v40 offset:288
	ds_read_b128 v[212:215], v40 offset:304
	s_waitcnt lgkmcnt(9)
	v_pk_fma_f32 v[134:135], v[42:43], v[64:65], 0 op_sel_hi:[0,1,0]
	v_pk_fma_f32 v[42:43], v[42:43], v[12:13], 0 op_sel:[1,0,0] op_sel_hi:[1,1,0]
	v_pk_fma_f32 v[134:135], v[44:45], v[66:67], v[134:135] op_sel_hi:[0,1,1]
	v_mov_b32_e32 v44, v45
	v_pk_fma_f32 v[42:43], v[44:45], v[14:15], v[42:43] op_sel_hi:[0,1,1]
	s_waitcnt lgkmcnt(8)
	v_pk_fma_f32 v[44:45], v[122:123], v[68:69], v[134:135] op_sel_hi:[0,1,1]
	v_pk_fma_f32 v[42:43], v[122:123], v[8:9], v[42:43] op_sel:[1,0,0]
	v_mov_b32_e32 v122, v125
	v_pk_fma_f32 v[44:45], v[124:125], v[70:71], v[44:45] op_sel_hi:[0,1,1]
	v_pk_fma_f32 v[42:43], v[122:123], v[10:11], v[42:43] op_sel_hi:[0,1,1]
	s_waitcnt lgkmcnt(7)
	v_pk_fma_f32 v[44:45], v[126:127], v[72:73], v[44:45] op_sel_hi:[0,1,1]
	v_pk_fma_f32 v[42:43], v[126:127], v[4:5], v[42:43] op_sel:[1,0,0]
	v_mov_b32_e32 v122, v129
	v_pk_fma_f32 v[44:45], v[128:129], v[74:75], v[44:45] op_sel_hi:[0,1,1]
	v_pk_fma_f32 v[42:43], v[122:123], v[6:7], v[42:43] op_sel_hi:[0,1,1]
	s_waitcnt lgkmcnt(6)
	v_pk_fma_f32 v[44:45], v[130:131], v[76:77], v[44:45] op_sel_hi:[0,1,1]
	v_pk_fma_f32 v[42:43], v[130:131], v[0:1], v[42:43] op_sel:[1,0,0]
	v_mov_b32_e32 v122, v133
	v_pk_fma_f32 v[44:45], v[132:133], v[78:79], v[44:45] op_sel_hi:[0,1,1]
	v_pk_fma_f32 v[42:43], v[122:123], v[2:3], v[42:43] op_sel_hi:[0,1,1]
	v_pk_add_f32 v[42:43], v[42:43], v[44:45]
	v_pk_mul_f32 v[44:45], v[50:51], v[46:47]
	s_nop 0
	v_pk_fma_f32 v[44:45], v[60:61], v[86:87], v[44:45] neg_lo:[0,0,1] neg_hi:[0,0,1]
	s_nop 0
	v_pk_add_f32 v[134:135], v[44:45], v[42:43]
	v_pk_mul_f32 v[44:45], v[50:51], v[86:87]
	v_bfe_u32 v41, v134, 16, 1
	v_pk_fma_f32 v[44:45], v[60:61], v[46:47], v[44:45]
	v_add3_u32 v41, v134, v41, s29
	v_pk_add_f32 v[46:47], v[44:45], v[42:43] op_sel:[0,1] op_sel_hi:[1,0]
	ds_write_b16_d16_hi v88, v41 offset:816
	v_bfe_u32 v41, v46, 16, 1
	v_add3_u32 v41, v46, v41, s29
	ds_write_b16_d16_hi v88, v41 offset:944
	ds_read_b128 v[42:45], v40 offset:320
	ds_read_b128 v[122:125], v40 offset:336
	ds_read_b128 v[126:129], v40 offset:352
	ds_read_b128 v[130:133], v40 offset:368
	s_waitcnt lgkmcnt(9)
	v_pk_fma_f32 v[86:87], v[200:201], v[64:65], 0 op_sel_hi:[0,1,0]
	v_pk_fma_f32 v[200:201], v[200:201], v[12:13], 0 op_sel:[1,0,0] op_sel_hi:[1,1,0]
	v_pk_fma_f32 v[86:87], v[202:203], v[66:67], v[86:87] op_sel_hi:[0,1,1]
	v_mov_b32_e32 v202, v203
	v_pk_fma_f32 v[200:201], v[202:203], v[14:15], v[200:201] op_sel_hi:[0,1,1]
	s_waitcnt lgkmcnt(8)
	v_pk_fma_f32 v[202:203], v[204:205], v[68:69], v[86:87] op_sel_hi:[0,1,1]
	v_pk_fma_f32 v[200:201], v[204:205], v[8:9], v[200:201] op_sel:[1,0,0]
	v_mov_b32_e32 v86, v207
	v_pk_fma_f32 v[202:203], v[206:207], v[70:71], v[202:203] op_sel_hi:[0,1,1]
	v_pk_fma_f32 v[200:201], v[86:87], v[10:11], v[200:201] op_sel_hi:[0,1,1]
	s_waitcnt lgkmcnt(7)
	v_pk_fma_f32 v[202:203], v[208:209], v[72:73], v[202:203] op_sel_hi:[0,1,1]
	v_pk_fma_f32 v[200:201], v[208:209], v[4:5], v[200:201] op_sel:[1,0,0]
	v_mov_b32_e32 v86, v211
	v_pk_fma_f32 v[202:203], v[210:211], v[74:75], v[202:203] op_sel_hi:[0,1,1]
	v_pk_fma_f32 v[200:201], v[86:87], v[6:7], v[200:201] op_sel_hi:[0,1,1]
	s_waitcnt lgkmcnt(6)
	v_pk_fma_f32 v[202:203], v[212:213], v[76:77], v[202:203] op_sel_hi:[0,1,1]
	v_pk_fma_f32 v[200:201], v[212:213], v[0:1], v[200:201] op_sel:[1,0,0]
	v_mov_b32_e32 v86, v215
	v_pk_fma_f32 v[202:203], v[214:215], v[78:79], v[202:203] op_sel_hi:[0,1,1]
	v_pk_fma_f32 v[200:201], v[86:87], v[2:3], v[200:201] op_sel_hi:[0,1,1]
	v_pk_add_f32 v[200:201], v[200:201], v[202:203]
	v_pk_mul_f32 v[202:203], v[50:51], v[46:47]
	s_nop 0
	v_pk_fma_f32 v[202:203], v[60:61], v[134:135], v[202:203] neg_lo:[0,0,1] neg_hi:[0,0,1]
	s_nop 0
	v_pk_add_f32 v[86:87], v[202:203], v[200:201]
	v_pk_mul_f32 v[202:203], v[50:51], v[134:135]
	v_bfe_u32 v41, v86, 16, 1
	v_pk_fma_f32 v[202:203], v[60:61], v[46:47], v[202:203]
	v_add3_u32 v41, v86, v41, s29
	v_pk_add_f32 v[46:47], v[202:203], v[200:201] op_sel:[0,1] op_sel_hi:[1,0]
	ds_write_b16_d16_hi v88, v41 offset:1088
	v_bfe_u32 v41, v46, 16, 1
	v_add3_u32 v41, v46, v41, s29
	ds_write_b16_d16_hi v88, v41 offset:1216
	ds_read_b128 v[200:203], v40 offset:384
	ds_read_b128 v[204:207], v40 offset:400
	ds_read_b128 v[208:211], v40 offset:416
	ds_read_b128 v[212:215], v40 offset:432
	s_waitcnt lgkmcnt(9)
; #define LAS __attribute__((address_space(3)))
; __device__ __forceinline__ unsigned f2bf(float f) { unsigned u = __builtin_bit_cast(unsigned, f); return (u + 0x7fffu + ((u >> 16) & 1u)) >> 16; }
; __device__ __forceinline__ void s5_phase(LAS unsigned char* lds, const unsigned char* ws, const bf16_t* proj, const float* c_re, const float* c_im, const float* dskip, bf16_t* z,
;                                          int vcu, int G, int wave, int lane) {
;     ...
;             for (int k = 0; k < 32; ++k) {
;                 f32x2 xa = (f32x2){0.f, 0.f}, xb = (f32x2){0.f, 0.f};
; #pragma unroll
;                 for (int q = 0; q < 4; ++q) { const f32x4 u4 = *(const LAS f32x4*)(Uc + k * 16 + 4 * q);
;                     xa = __builtin_elementwise_fma((f32x2){u4[0], u4[0]}, (f32x2){bbre[4 * q], bbim[4 * q]}, xa);
;                     xb = __builtin_elementwise_fma((f32x2){u4[1], u4[1]}, (f32x2){bbre[4 * q + 1], bbim[4 * q + 1]}, xb);
;                     xa = __builtin_elementwise_fma((f32x2){u4[2], u4[2]}, (f32x2){bbre[4 * q + 2], bbim[4 * q + 2]}, xa);
;                     xb = __builtin_elementwise_fma((f32x2){u4[3], u4[3]}, (f32x2){bbre[4 * q + 3], bbim[4 * q + 3]}, xb); }
;                 const f32x2 xx = xa + xb;
;                 const float nr = are * hre - aim * him + xx[0], ni = are * him + aim * hre + xx[1]; hre = nr; him = ni;
;                 Hc[k * 136 + n] = (bf16_t)f2bf(hre); Hc[k * 136 + 64 + n] = (bf16_t)f2bf(him);
;             }
	v_pk_fma_f32 v[134:135], v[42:43], v[64:65], 0 op_sel_hi:[0,1,0]
	v_pk_fma_f32 v[42:43], v[42:43], v[12:13], 0 op_sel:[1,0,0] op_sel_hi:[1,1,0]
	v_pk_fma_f32 v[134:135], v[44:45], v[66:67], v[134:135] op_sel_hi:[0,1,1]
	v_mov_b32_e32 v44, v45
	v_pk_fma_f32 v[42:43], v[44:45], v[14:15], v[42:43] op_sel_hi:[0,1,1]
	s_waitcnt lgkmcnt(8)
	v_pk_fma_f32 v[44:45], v[122:123], v[68:69], v[134:135] op_sel_hi:[0,1,1]
	v_pk_fma_f32 v[42:43], v[122:123], v[8:9], v[42:43] op_sel:[1,0,0]
	v_mov_b32_e32 v122, v125
	v_pk_fma_f32 v[44:45], v[124:125], v[70:71], v[44:45] op_sel_hi:[0,1,1]
	v_pk_fma_f32 v[42:43], v[122:123], v[10:11], v[42:43] op_sel_hi:[0,1,1]
	s_waitcnt lgkmcnt(7)
	v_pk_fma_f32 v[44:45], v[126:127], v[72:73], v[44:45] op_sel_hi:[0,1,1]
	v_pk_fma_f32 v[42:43], v[126:127], v[4:5], v[42:43] op_sel:[1,0,0]
	v_mov_b32_e32 v122, v129
	v_pk_fma_f32 v[44:45], v[128:129], v[74:75], v[44:45] op_sel_hi:[0,1,1]
	v_pk_fma_f32 v[42:43], v[122:123], v[6:7], v[42:43] op_sel_hi:[0,1,1]
	s_waitcnt lgkmcnt(6)
	v_pk_fma_f32 v[44:45], v[130:131], v[76:77], v[44:45] op_sel_hi:[0,1,1]
	v_pk_fma_f32 v[42:43], v[130:131], v[0:1], v[42:43] op_sel:[1,0,0]
	v_mov_b32_e32 v122, v133
	v_pk_fma_f32 v[44:45], v[132:133], v[78:79], v[44:45] op_sel_hi:[0,1,1]
	v_pk_fma_f32 v[42:43], v[122:123], v[2:3], v[42:43] op_sel_hi:[0,1,1]
	v_pk_add_f32 v[42:43], v[42:43], v[44:45]
	v_pk_mul_f32 v[44:45], v[50:51], v[46:47]
	s_nop 0
	v_pk_fma_f32 v[44:45], v[60:61], v[86:87], v[44:45] neg_lo:[0,0,1] neg_hi:[0,0,1]
	s_nop 0
	v_pk_add_f32 v[134:135], v[44:45], v[42:43]
	v_pk_mul_f32 v[44:45], v[50:51], v[86:87]
	v_bfe_u32 v41, v134, 16, 1
	v_pk_fma_f32 v[44:45], v[60:61], v[46:47], v[44:45]
	v_add3_u32 v41, v134, v41, s29
	v_pk_add_f32 v[46:47], v[44:45], v[42:43] op_sel:[0,1] op_sel_hi:[1,0]
	ds_write_b16_d16_hi v88, v41 offset:1360
	v_bfe_u32 v41, v46, 16, 1
	v_add3_u32 v41, v46, v41, s29
	ds_write_b16_d16_hi v88, v41 offset:1488
	ds_read_b128 v[42:45], v40 offset:448
	ds_read_b128 v[122:125], v40 offset:464
	ds_read_b128 v[126:129], v40 offset:480
	ds_read_b128 v[130:133], v40 offset:496
	s_waitcnt lgkmcnt(9)
	v_pk_fma_f32 v[86:87], v[200:201], v[64:65], 0 op_sel_hi:[0,1,0]
	v_pk_fma_f32 v[200:201], v[200:201], v[12:13], 0 op_sel:[1,0,0] op_sel_hi:[1,1,0]
	v_pk_fma_f32 v[86:87], v[202:203], v[66:67], v[86:87] op_sel_hi:[0,1,1]
	v_mov_b32_e32 v202, v203
	v_pk_fma_f32 v[200:201], v[202:203], v[14:15], v[200:201] op_sel_hi:[0,1,1]
	s_waitcnt lgkmcnt(8)
	v_pk_fma_f32 v[202:203], v[204:205], v[68:69], v[86:87] op_sel_hi:[0,1,1]
	v_pk_fma_f32 v[200:201], v[204:205], v[8:9], v[200:201] op_sel:[1,0,0]
	v_mov_b32_e32 v86, v207
	v_pk_fma_f32 v[202:203], v[206:207], v[70:71], v[202:203] op_sel_hi:[0,1,1]
	v_pk_fma_f32 v[200:201], v[86:87], v[10:11], v[200:201] op_sel_hi:[0,1,1]
	s_waitcnt lgkmcnt(7)
	v_pk_fma_f32 v[202:203], v[208:209], v[72:73], v[202:203] op_sel_hi:[0,1,1]
	v_pk_fma_f32 v[200:201], v[208:209], v[4:5], v[200:201] op_sel:[1,0,0]
	v_mov_b32_e32 v86, v211
	v_pk_fma_f32 v[202:203], v[210:211], v[74:75], v[202:203] op_sel_hi:[0,1,1]
	v_pk_fma_f32 v[200:201], v[86:87], v[6:7], v[200:201] op_sel_hi:[0,1,1]
	s_waitcnt lgkmcnt(6)
	v_pk_fma_f32 v[202:203], v[212:213], v[76:77], v[202:203] op_sel_hi:[0,1,1]
	v_pk_fma_f32 v[200:201], v[212:213], v[0:1], v[200:201] op_sel:[1,0,0]
	v_mov_b32_e32 v86, v215
	v_pk_fma_f32 v[202:203], v[214:215], v[78:79], v[202:203] op_sel_hi:[0,1,1]
	v_pk_fma_f32 v[200:201], v[86:87], v[2:3], v[200:201] op_sel_hi:[0,1,1]
	v_pk_add_f32 v[200:201], v[200:201], v[202:203]
	v_pk_mul_f32 v[202:203], v[50:51], v[46:47]
	s_nop 0
	v_pk_fma_f32 v[202:203], v[60:61], v[134:135], v[202:203] neg_lo:[0,0,1] neg_hi:[0,0,1]
	s_nop 0
	v_pk_add_f32 v[86:87], v[202:203], v[200:201]
	v_pk_mul_f32 v[202:203], v[50:51], v[134:135]
	v_bfe_u32 v41, v86, 16, 1
	v_pk_fma_f32 v[202:203], v[60:61], v[46:47], v[202:203]
	v_add3_u32 v41, v86, v41, s29
	v_pk_add_f32 v[46:47], v[202:203], v[200:201] op_sel:[0,1] op_sel_hi:[1,0]
	ds_write_b16_d16_hi v88, v41 offset:1632
	v_bfe_u32 v41, v46, 16, 1
	v_add3_u32 v41, v46, v41, s29
	ds_write_b16_d16_hi v88, v41 offset:1760
	ds_read_b128 v[200:203], v40 offset:512
	ds_read_b128 v[204:207], v40 offset:528
	ds_read_b128 v[208:211], v40 offset:544
	ds_read_b128 v[212:215], v40 offset:560
	s_waitcnt lgkmcnt(9)
	v_pk_fma_f32 v[134:135], v[42:43], v[64:65], 0 op_sel_hi:[0,1,0]
	v_pk_fma_f32 v[42:43], v[42:43], v[12:13], 0 op_sel:[1,0,0] op_sel_hi:[1,1,0]
	v_pk_fma_f32 v[134:135], v[44:45], v[66:67], v[134:135] op_sel_hi:[0,1,1]
	v_mov_b32_e32 v44, v45
	v_pk_fma_f32 v[42:43], v[44:45], v[14:15], v[42:43] op_sel_hi:[0,1,1]
	s_waitcnt lgkmcnt(8)
	v_pk_fma_f32 v[44:45], v[122:123], v[68:69], v[134:135] op_sel_hi:[0,1,1]
	v_pk_fma_f32 v[42:43], v[122:123], v[8:9], v[42:43] op_sel:[1,0,0]
	v_mov_b32_e32 v122, v125
	v_pk_fma_f32 v[44:45], v[124:125], v[70:71], v[44:45] op_sel_hi:[0,1,1]
	v_pk_fma_f32 v[42:43], v[122:123], v[10:11], v[42:43] op_sel_hi:[0,1,1]
	s_waitcnt lgkmcnt(7)
	v_pk_fma_f32 v[44:45], v[126:127], v[72:73], v[44:45] op_sel_hi:[0,1,1]
	v_pk_fma_f32 v[42:43], v[126:127], v[4:5], v[42:43] op_sel:[1,0,0]
	v_mov_b32_e32 v122, v129
	v_pk_fma_f32 v[44:45], v[128:129], v[74:75], v[44:45] op_sel_hi:[0,1,1]
	v_pk_fma_f32 v[42:43], v[122:123], v[6:7], v[42:43] op_sel_hi:[0,1,1]
	s_waitcnt lgkmcnt(6)
; #define LAS __attribute__((address_space(3)))
; __device__ __forceinline__ unsigned f2bf(float f) { unsigned u = __builtin_bit_cast(unsigned, f); return (u + 0x7fffu + ((u >> 16) & 1u)) >> 16; }
; __device__ __forceinline__ void s5_phase(LAS unsigned char* lds, const unsigned char* ws, const bf16_t* proj, const float* c_re, const float* c_im, const float* dskip, bf16_t* z,
;                                          int vcu, int G, int wave, int lane) {
;     ...
;             for (int k = 0; k < 32; ++k) {
;                 f32x2 xa = (f32x2){0.f, 0.f}, xb = (f32x2){0.f, 0.f};
; #pragma unroll
;                 for (int q = 0; q < 4; ++q) { const f32x4 u4 = *(const LAS f32x4*)(Uc + k * 16 + 4 * q);
;                     xa = __builtin_elementwise_fma((f32x2){u4[0], u4[0]}, (f32x2){bbre[4 * q], bbim[4 * q]}, xa);
;                     xb = __builtin_elementwise_fma((f32x2){u4[1], u4[1]}, (f32x2){bbre[4 * q + 1], bbim[4 * q + 1]}, xb);
;                     xa = __builtin_elementwise_fma((f32x2){u4[2], u4[2]}, (f32x2){bbre[4 * q + 2], bbim[4 * q + 2]}, xa);
;                     xb = __builtin_elementwise_fma((f32x2){u4[3], u4[3]}, (f32x2){bbre[4 * q + 3], bbim[4 * q + 3]}, xb); }
;                 const f32x2 xx = xa + xb;
;                 const float nr = are * hre - aim * him + xx[0], ni = are * him + aim * hre + xx[1]; hre = nr; him = ni;
;                 Hc[k * 136 + n] = (bf16_t)f2bf(hre); Hc[k * 136 + 64 + n] = (bf16_t)f2bf(him);
;             }
	v_pk_fma_f32 v[44:45], v[130:131], v[76:77], v[44:45] op_sel_hi:[0,1,1]
	v_pk_fma_f32 v[42:43], v[130:131], v[0:1], v[42:43] op_sel:[1,0,0]
	v_mov_b32_e32 v122, v133
	v_pk_fma_f32 v[44:45], v[132:133], v[78:79], v[44:45] op_sel_hi:[0,1,1]
	v_pk_fma_f32 v[42:43], v[122:123], v[2:3], v[42:43] op_sel_hi:[0,1,1]
	v_pk_add_f32 v[42:43], v[42:43], v[44:45]
	v_pk_mul_f32 v[44:45], v[50:51], v[46:47]
	s_nop 0
	v_pk_fma_f32 v[44:45], v[60:61], v[86:87], v[44:45] neg_lo:[0,0,1] neg_hi:[0,0,1]
	s_nop 0
	v_pk_add_f32 v[134:135], v[44:45], v[42:43]
	v_pk_mul_f32 v[44:45], v[50:51], v[86:87]
	v_bfe_u32 v41, v134, 16, 1
	v_pk_fma_f32 v[44:45], v[60:61], v[46:47], v[44:45]
	v_add3_u32 v41, v134, v41, s29
	v_pk_add_f32 v[46:47], v[44:45], v[42:43] op_sel:[0,1] op_sel_hi:[1,0]
	ds_write_b16_d16_hi v88, v41 offset:1904
	v_bfe_u32 v41, v46, 16, 1
	v_add3_u32 v41, v46, v41, s29
	ds_write_b16_d16_hi v88, v41 offset:2032
	ds_read_b128 v[42:45], v40 offset:576
	ds_read_b128 v[122:125], v40 offset:592
	ds_read_b128 v[126:129], v40 offset:608
	ds_read_b128 v[130:133], v40 offset:624
	s_waitcnt lgkmcnt(9)
	v_pk_fma_f32 v[86:87], v[200:201], v[64:65], 0 op_sel_hi:[0,1,0]
	v_pk_fma_f32 v[200:201], v[200:201], v[12:13], 0 op_sel:[1,0,0] op_sel_hi:[1,1,0]
	v_pk_fma_f32 v[86:87], v[202:203], v[66:67], v[86:87] op_sel_hi:[0,1,1]
	v_mov_b32_e32 v202, v203
	v_pk_fma_f32 v[200:201], v[202:203], v[14:15], v[200:201] op_sel_hi:[0,1,1]
	s_waitcnt lgkmcnt(8)
	v_pk_fma_f32 v[202:203], v[204:205], v[68:69], v[86:87] op_sel_hi:[0,1,1]
	v_pk_fma_f32 v[200:201], v[204:205], v[8:9], v[200:201] op_sel:[1,0,0]
	v_mov_b32_e32 v86, v207
	v_pk_fma_f32 v[202:203], v[206:207], v[70:71], v[202:203] op_sel_hi:[0,1,1]
	v_pk_fma_f32 v[200:201], v[86:87], v[10:11], v[200:201] op_sel_hi:[0,1,1]
	s_waitcnt lgkmcnt(7)
	v_pk_fma_f32 v[202:203], v[208:209], v[72:73], v[202:203] op_sel_hi:[0,1,1]
	v_pk_fma_f32 v[200:201], v[208:209], v[4:5], v[200:201] op_sel:[1,0,0]
	v_mov_b32_e32 v86, v211
	v_pk_fma_f32 v[202:203], v[210:211], v[74:75], v[202:203] op_sel_hi:[0,1,1]
	v_pk_fma_f32 v[200:201], v[86:87], v[6:7], v[200:201] op_sel_hi:[0,1,1]
	s_waitcnt lgkmcnt(6)
	v_pk_fma_f32 v[202:203], v[212:213], v[76:77], v[202:203] op_sel_hi:[0,1,1]
	v_pk_fma_f32 v[200:201], v[212:213], v[0:1], v[200:201] op_sel:[1,0,0]
	v_mov_b32_e32 v86, v215
	v_pk_fma_f32 v[202:203], v[214:215], v[78:79], v[202:203] op_sel_hi:[0,1,1]
	v_pk_fma_f32 v[200:201], v[86:87], v[2:3], v[200:201] op_sel_hi:[0,1,1]
	v_pk_add_f32 v[200:201], v[200:201], v[202:203]
	v_pk_mul_f32 v[202:203], v[50:51], v[46:47]
	s_nop 0
	v_pk_fma_f32 v[202:203], v[60:61], v[134:135], v[202:203] neg_lo:[0,0,1] neg_hi:[0,0,1]
	s_nop 0
	v_pk_add_f32 v[86:87], v[202:203], v[200:201]
	v_pk_mul_f32 v[202:203], v[50:51], v[134:135]
	v_bfe_u32 v41, v86, 16, 1
	v_pk_fma_f32 v[202:203], v[60:61], v[46:47], v[202:203]
	v_add3_u32 v41, v86, v41, s29
	v_pk_add_f32 v[46:47], v[202:203], v[200:201] op_sel:[0,1] op_sel_hi:[1,0]
	ds_write_b16_d16_hi v88, v41 offset:2176
	v_bfe_u32 v41, v46, 16, 1
	v_add3_u32 v41, v46, v41, s29
	ds_write_b16_d16_hi v88, v41 offset:2304
	ds_read_b128 v[200:203], v40 offset:640
	ds_read_b128 v[204:207], v40 offset:656
	ds_read_b128 v[208:211], v40 offset:672
	ds_read_b128 v[212:215], v40 offset:688
	s_waitcnt lgkmcnt(9)
	v_pk_fma_f32 v[134:135], v[42:43], v[64:65], 0 op_sel_hi:[0,1,0]
	v_pk_fma_f32 v[42:43], v[42:43], v[12:13], 0 op_sel:[1,0,0] op_sel_hi:[1,1,0]
	v_pk_fma_f32 v[134:135], v[44:45], v[66:67], v[134:135] op_sel_hi:[0,1,1]
	v_mov_b32_e32 v44, v45
	v_pk_fma_f32 v[42:43], v[44:45], v[14:15], v[42:43] op_sel_hi:[0,1,1]
	s_waitcnt lgkmcnt(8)
	v_pk_fma_f32 v[44:45], v[122:123], v[68:69], v[134:135] op_sel_hi:[0,1,1]
	v_pk_fma_f32 v[42:43], v[122:123], v[8:9], v[42:43] op_sel:[1,0,0]
	v_mov_b32_e32 v122, v125
	v_pk_fma_f32 v[44:45], v[124:125], v[70:71], v[44:45] op_sel_hi:[0,1,1]
	v_pk_fma_f32 v[42:43], v[122:123], v[10:11], v[42:43] op_sel_hi:[0,1,1]
	s_waitcnt lgkmcnt(7)
	v_pk_fma_f32 v[44:45], v[126:127], v[72:73], v[44:45] op_sel_hi:[0,1,1]
	v_pk_fma_f32 v[42:43], v[126:127], v[4:5], v[42:43] op_sel:[1,0,0]
	v_mov_b32_e32 v122, v129
	v_pk_fma_f32 v[44:45], v[128:129], v[74:75], v[44:45] op_sel_hi:[0,1,1]
	v_pk_fma_f32 v[42:43], v[122:123], v[6:7], v[42:43] op_sel_hi:[0,1,1]
	s_waitcnt lgkmcnt(6)
	v_pk_fma_f32 v[44:45], v[130:131], v[76:77], v[44:45] op_sel_hi:[0,1,1]
	v_pk_fma_f32 v[42:43], v[130:131], v[0:1], v[42:43] op_sel:[1,0,0]
	v_mov_b32_e32 v122, v133
	v_pk_fma_f32 v[44:45], v[132:133], v[78:79], v[44:45] op_sel_hi:[0,1,1]
	v_pk_fma_f32 v[42:43], v[122:123], v[2:3], v[42:43] op_sel_hi:[0,1,1]
	v_pk_add_f32 v[42:43], v[42:43], v[44:45]
	v_pk_mul_f32 v[44:45], v[50:51], v[46:47]
	s_nop 0
	v_pk_fma_f32 v[44:45], v[60:61], v[86:87], v[44:45] neg_lo:[0,0,1] neg_hi:[0,0,1]
	s_nop 0
	v_pk_add_f32 v[134:135], v[44:45], v[42:43]
	v_pk_mul_f32 v[44:45], v[50:51], v[86:87]
	v_bfe_u32 v41, v134, 16, 1
	v_pk_fma_f32 v[44:45], v[60:61], v[46:47], v[44:45]
	v_add3_u32 v41, v134, v41, s29
	v_pk_add_f32 v[46:47], v[44:45], v[42:43] op_sel:[0,1] op_sel_hi:[1,0]
	ds_write_b16_d16_hi v88, v41 offset:2448
	v_bfe_u32 v41, v46, 16, 1
	v_add3_u32 v41, v46, v41, s29
	ds_write_b16_d16_hi v88, v41 offset:2576
	ds_read_b128 v[42:45], v40 offset:704
	ds_read_b128 v[122:125], v40 offset:720
	ds_read_b128 v[126:129], v40 offset:736
	ds_read_b128 v[130:133], v40 offset:752
	s_waitcnt lgkmcnt(9)
	v_pk_fma_f32 v[86:87], v[200:201], v[64:65], 0 op_sel_hi:[0,1,0]
	v_pk_fma_f32 v[200:201], v[200:201], v[12:13], 0 op_sel:[1,0,0] op_sel_hi:[1,1,0]
	v_pk_fma_f32 v[86:87], v[202:203], v[66:67], v[86:87] op_sel_hi:[0,1,1]
	v_mov_b32_e32 v202, v203
	v_pk_fma_f32 v[200:201], v[202:203], v[14:15], v[200:201] op_sel_hi:[0,1,1]
	s_waitcnt lgkmcnt(8)
; #define LAS __attribute__((address_space(3)))
; __device__ __forceinline__ unsigned f2bf(float f) { unsigned u = __builtin_bit_cast(unsigned, f); return (u + 0x7fffu + ((u >> 16) & 1u)) >> 16; }
; __device__ __forceinline__ void s5_phase(LAS unsigned char* lds, const unsigned char* ws, const bf16_t* proj, const float* c_re, const float* c_im, const float* dskip, bf16_t* z,
;                                          int vcu, int G, int wave, int lane) {
;     ...
;             for (int k = 0; k < 32; ++k) {
;                 f32x2 xa = (f32x2){0.f, 0.f}, xb = (f32x2){0.f, 0.f};
; #pragma unroll
;                 for (int q = 0; q < 4; ++q) { const f32x4 u4 = *(const LAS f32x4*)(Uc + k * 16 + 4 * q);
;                     xa = __builtin_elementwise_fma((f32x2){u4[0], u4[0]}, (f32x2){bbre[4 * q], bbim[4 * q]}, xa);
;                     xb = __builtin_elementwise_fma((f32x2){u4[1], u4[1]}, (f32x2){bbre[4 * q + 1], bbim[4 * q + 1]}, xb);
;                     xa = __builtin_elementwise_fma((f32x2){u4[2], u4[2]}, (f32x2){bbre[4 * q + 2], bbim[4 * q + 2]}, xa);
;                     xb = __builtin_elementwise_fma((f32x2){u4[3], u4[3]}, (f32x2){bbre[4 * q + 3], bbim[4 * q + 3]}, xb); }
;                 const f32x2 xx = xa + xb;
;                 const float nr = are * hre - aim * him + xx[0], ni = are * him + aim * hre + xx[1]; hre = nr; him = ni;
;                 Hc[k * 136 + n] = (bf16_t)f2bf(hre); Hc[k * 136 + 64 + n] = (bf16_t)f2bf(him);
;             }
	v_pk_fma_f32 v[202:203], v[204:205], v[68:69], v[86:87] op_sel_hi:[0,1,1]
	v_pk_fma_f32 v[200:201], v[204:205], v[8:9], v[200:201] op_sel:[1,0,0]
	v_mov_b32_e32 v86, v207
	v_pk_fma_f32 v[202:203], v[206:207], v[70:71], v[202:203] op_sel_hi:[0,1,1]
	v_pk_fma_f32 v[200:201], v[86:87], v[10:11], v[200:201] op_sel_hi:[0,1,1]
	s_waitcnt lgkmcnt(7)
	v_pk_fma_f32 v[202:203], v[208:209], v[72:73], v[202:203] op_sel_hi:[0,1,1]
	v_pk_fma_f32 v[200:201], v[208:209], v[4:5], v[200:201] op_sel:[1,0,0]
	v_mov_b32_e32 v86, v211
	v_pk_fma_f32 v[202:203], v[210:211], v[74:75], v[202:203] op_sel_hi:[0,1,1]
	v_pk_fma_f32 v[200:201], v[86:87], v[6:7], v[200:201] op_sel_hi:[0,1,1]
	s_waitcnt lgkmcnt(6)
	v_pk_fma_f32 v[202:203], v[212:213], v[76:77], v[202:203] op_sel_hi:[0,1,1]
	v_pk_fma_f32 v[200:201], v[212:213], v[0:1], v[200:201] op_sel:[1,0,0]
	v_mov_b32_e32 v86, v215
	v_pk_fma_f32 v[202:203], v[214:215], v[78:79], v[202:203] op_sel_hi:[0,1,1]
	v_pk_fma_f32 v[200:201], v[86:87], v[2:3], v[200:201] op_sel_hi:[0,1,1]
	v_pk_add_f32 v[200:201], v[200:201], v[202:203]
	v_pk_mul_f32 v[202:203], v[50:51], v[46:47]
	s_nop 0
	v_pk_fma_f32 v[202:203], v[60:61], v[134:135], v[202:203] neg_lo:[0,0,1] neg_hi:[0,0,1]
	s_nop 0
	v_pk_add_f32 v[86:87], v[202:203], v[200:201]
	v_pk_mul_f32 v[202:203], v[50:51], v[134:135]
	v_bfe_u32 v41, v86, 16, 1
	v_pk_fma_f32 v[202:203], v[60:61], v[46:47], v[202:203]
	v_add3_u32 v41, v86, v41, s29
	v_pk_add_f32 v[46:47], v[202:203], v[200:201] op_sel:[0,1] op_sel_hi:[1,0]
	ds_write_b16_d16_hi v88, v41 offset:2720
	v_bfe_u32 v41, v46, 16, 1
	v_add3_u32 v41, v46, v41, s29
	ds_write_b16_d16_hi v88, v41 offset:2848
	ds_read_b128 v[200:203], v40 offset:768
	ds_read_b128 v[204:207], v40 offset:784
	ds_read_b128 v[208:211], v40 offset:800
	ds_read_b128 v[212:215], v40 offset:816
	s_waitcnt lgkmcnt(9)
	v_pk_fma_f32 v[134:135], v[42:43], v[64:65], 0 op_sel_hi:[0,1,0]
	v_pk_fma_f32 v[42:43], v[42:43], v[12:13], 0 op_sel:[1,0,0] op_sel_hi:[1,1,0]
	v_pk_fma_f32 v[134:135], v[44:45], v[66:67], v[134:135] op_sel_hi:[0,1,1]
	v_mov_b32_e32 v44, v45
	v_pk_fma_f32 v[42:43], v[44:45], v[14:15], v[42:43] op_sel_hi:[0,1,1]
	s_waitcnt lgkmcnt(8)
	v_pk_fma_f32 v[44:45], v[122:123], v[68:69], v[134:135] op_sel_hi:[0,1,1]
	v_pk_fma_f32 v[42:43], v[122:123], v[8:9], v[42:43] op_sel:[1,0,0]
	v_mov_b32_e32 v122, v125
	v_pk_fma_f32 v[44:45], v[124:125], v[70:71], v[44:45] op_sel_hi:[0,1,1]
	v_pk_fma_f32 v[42:43], v[122:123], v[10:11], v[42:43] op_sel_hi:[0,1,1]
	s_waitcnt lgkmcnt(7)
	v_pk_fma_f32 v[44:45], v[126:127], v[72:73], v[44:45] op_sel_hi:[0,1,1]
	v_pk_fma_f32 v[42:43], v[126:127], v[4:5], v[42:43] op_sel:[1,0,0]
	v_mov_b32_e32 v122, v129
	v_pk_fma_f32 v[44:45], v[128:129], v[74:75], v[44:45] op_sel_hi:[0,1,1]
	v_pk_fma_f32 v[42:43], v[122:123], v[6:7], v[42:43] op_sel_hi:[0,1,1]
	s_waitcnt lgkmcnt(6)
	v_pk_fma_f32 v[44:45], v[130:131], v[76:77], v[44:45] op_sel_hi:[0,1,1]
	v_pk_fma_f32 v[42:43], v[130:131], v[0:1], v[42:43] op_sel:[1,0,0]
	v_mov_b32_e32 v122, v133
	v_pk_fma_f32 v[44:45], v[132:133], v[78:79], v[44:45] op_sel_hi:[0,1,1]
	v_pk_fma_f32 v[42:43], v[122:123], v[2:3], v[42:43] op_sel_hi:[0,1,1]
	v_pk_add_f32 v[42:43], v[42:43], v[44:45]
	v_pk_mul_f32 v[44:45], v[50:51], v[46:47]
	s_nop 0
	v_pk_fma_f32 v[44:45], v[60:61], v[86:87], v[44:45] neg_lo:[0,0,1] neg_hi:[0,0,1]
	s_nop 0
	v_pk_add_f32 v[134:135], v[44:45], v[42:43]
	v_pk_mul_f32 v[44:45], v[50:51], v[86:87]
	v_bfe_u32 v41, v134, 16, 1
	v_pk_fma_f32 v[44:45], v[60:61], v[46:47], v[44:45]
	v_add3_u32 v41, v134, v41, s29
	v_pk_add_f32 v[46:47], v[44:45], v[42:43] op_sel:[0,1] op_sel_hi:[1,0]
	ds_write_b16_d16_hi v88, v41 offset:2992
	v_bfe_u32 v41, v46, 16, 1
	v_add3_u32 v41, v46, v41, s29
	ds_write_b16_d16_hi v88, v41 offset:3120
	ds_read_b128 v[42:45], v40 offset:832
	ds_read_b128 v[122:125], v40 offset:848
	ds_read_b128 v[126:129], v40 offset:864
	ds_read_b128 v[130:133], v40 offset:880
	s_waitcnt lgkmcnt(9)
	v_pk_fma_f32 v[86:87], v[200:201], v[64:65], 0 op_sel_hi:[0,1,0]
	v_pk_fma_f32 v[200:201], v[200:201], v[12:13], 0 op_sel:[1,0,0] op_sel_hi:[1,1,0]
	v_pk_fma_f32 v[86:87], v[202:203], v[66:67], v[86:87] op_sel_hi:[0,1,1]
	v_mov_b32_e32 v202, v203
	v_pk_fma_f32 v[200:201], v[202:203], v[14:15], v[200:201] op_sel_hi:[0,1,1]
	s_waitcnt lgkmcnt(8)
	v_pk_fma_f32 v[202:203], v[204:205], v[68:69], v[86:87] op_sel_hi:[0,1,1]
	v_pk_fma_f32 v[200:201], v[204:205], v[8:9], v[200:201] op_sel:[1,0,0]
	v_mov_b32_e32 v86, v207
	v_pk_fma_f32 v[202:203], v[206:207], v[70:71], v[202:203] op_sel_hi:[0,1,1]
	v_pk_fma_f32 v[200:201], v[86:87], v[10:11], v[200:201] op_sel_hi:[0,1,1]
	s_waitcnt lgkmcnt(7)
	v_pk_fma_f32 v[202:203], v[208:209], v[72:73], v[202:203] op_sel_hi:[0,1,1]
	v_pk_fma_f32 v[200:201], v[208:209], v[4:5], v[200:201] op_sel:[1,0,0]
	v_mov_b32_e32 v86, v211
	v_pk_fma_f32 v[202:203], v[210:211], v[74:75], v[202:203] op_sel_hi:[0,1,1]
	v_pk_fma_f32 v[200:201], v[86:87], v[6:7], v[200:201] op_sel_hi:[0,1,1]
	s_waitcnt lgkmcnt(6)
	v_pk_fma_f32 v[202:203], v[212:213], v[76:77], v[202:203] op_sel_hi:[0,1,1]
	v_pk_fma_f32 v[200:201], v[212:213], v[0:1], v[200:201] op_sel:[1,0,0]
	v_mov_b32_e32 v86, v215
	v_pk_fma_f32 v[202:203], v[214:215], v[78:79], v[202:203] op_sel_hi:[0,1,1]
	v_pk_fma_f32 v[200:201], v[86:87], v[2:3], v[200:201] op_sel_hi:[0,1,1]
	v_pk_add_f32 v[200:201], v[200:201], v[202:203]
	v_pk_mul_f32 v[202:203], v[50:51], v[46:47]
	s_nop 0
	v_pk_fma_f32 v[202:203], v[60:61], v[134:135], v[202:203] neg_lo:[0,0,1] neg_hi:[0,0,1]
	s_nop 0
	v_pk_add_f32 v[86:87], v[202:203], v[200:201]
	v_pk_mul_f32 v[202:203], v[50:51], v[134:135]
	v_bfe_u32 v41, v86, 16, 1
	v_pk_fma_f32 v[202:203], v[60:61], v[46:47], v[202:203]
	v_add3_u32 v41, v86, v41, s29
	v_pk_add_f32 v[46:47], v[202:203], v[200:201] op_sel:[0,1] op_sel_hi:[1,0]
	ds_write_b16_d16_hi v88, v41 offset:3264
	v_bfe_u32 v41, v46, 16, 1
	v_add3_u32 v41, v46, v41, s29
	ds_write_b16_d16_hi v88, v41 offset:3392
	ds_read_b128 v[200:203], v40 offset:896
	ds_read_b128 v[204:207], v40 offset:912
	ds_read_b128 v[208:211], v40 offset:928
	ds_read_b128 v[212:215], v40 offset:944
	s_waitcnt lgkmcnt(9)
; #define LAS __attribute__((address_space(3)))
; __device__ __forceinline__ unsigned f2bf(float f) { unsigned u = __builtin_bit_cast(unsigned, f); return (u + 0x7fffu + ((u >> 16) & 1u)) >> 16; }
; __device__ __forceinline__ void s5_phase(LAS unsigned char* lds, const unsigned char* ws, const bf16_t* proj, const float* c_re, const float* c_im, const float* dskip, bf16_t* z,
;                                          int vcu, int G, int wave, int lane) {
;     ...
;             for (int k = 0; k < 32; ++k) {
;                 f32x2 xa = (f32x2){0.f, 0.f}, xb = (f32x2){0.f, 0.f};
; #pragma unroll
;                 for (int q = 0; q < 4; ++q) { const f32x4 u4 = *(const LAS f32x4*)(Uc + k * 16 + 4 * q);
;                     xa = __builtin_elementwise_fma((f32x2){u4[0], u4[0]}, (f32x2){bbre[4 * q], bbim[4 * q]}, xa);
;                     xb = __builtin_elementwise_fma((f32x2){u4[1], u4[1]}, (f32x2){bbre[4 * q + 1], bbim[4 * q + 1]}, xb);
;                     xa = __builtin_elementwise_fma((f32x2){u4[2], u4[2]}, (f32x2){bbre[4 * q + 2], bbim[4 * q + 2]}, xa);
;                     xb = __builtin_elementwise_fma((f32x2){u4[3], u4[3]}, (f32x2){bbre[4 * q + 3], bbim[4 * q + 3]}, xb); }
;                 const f32x2 xx = xa + xb;
;                 const float nr = are * hre - aim * him + xx[0], ni = are * him + aim * hre + xx[1]; hre = nr; him = ni;
;                 Hc[k * 136 + n] = (bf16_t)f2bf(hre); Hc[k * 136 + 64 + n] = (bf16_t)f2bf(him);
;             }
	v_pk_fma_f32 v[134:135], v[42:43], v[64:65], 0 op_sel_hi:[0,1,0]
	v_pk_fma_f32 v[42:43], v[42:43], v[12:13], 0 op_sel:[1,0,0] op_sel_hi:[1,1,0]
	v_pk_fma_f32 v[134:135], v[44:45], v[66:67], v[134:135] op_sel_hi:[0,1,1]
	v_mov_b32_e32 v44, v45
	v_pk_fma_f32 v[42:43], v[44:45], v[14:15], v[42:43] op_sel_hi:[0,1,1]
	s_waitcnt lgkmcnt(8)
	v_pk_fma_f32 v[44:45], v[122:123], v[68:69], v[134:135] op_sel_hi:[0,1,1]
	v_pk_fma_f32 v[42:43], v[122:123], v[8:9], v[42:43] op_sel:[1,0,0]
	v_mov_b32_e32 v122, v125
	v_pk_fma_f32 v[44:45], v[124:125], v[70:71], v[44:45] op_sel_hi:[0,1,1]
	v_pk_fma_f32 v[42:43], v[122:123], v[10:11], v[42:43] op_sel_hi:[0,1,1]
	s_waitcnt lgkmcnt(7)
	v_pk_fma_f32 v[44:45], v[126:127], v[72:73], v[44:45] op_sel_hi:[0,1,1]
	v_pk_fma_f32 v[42:43], v[126:127], v[4:5], v[42:43] op_sel:[1,0,0]
	v_mov_b32_e32 v122, v129
	v_pk_fma_f32 v[44:45], v[128:129], v[74:75], v[44:45] op_sel_hi:[0,1,1]
	v_pk_fma_f32 v[42:43], v[122:123], v[6:7], v[42:43] op_sel_hi:[0,1,1]
	s_waitcnt lgkmcnt(6)
	v_pk_fma_f32 v[44:45], v[130:131], v[76:77], v[44:45] op_sel_hi:[0,1,1]
	v_pk_fma_f32 v[42:43], v[130:131], v[0:1], v[42:43] op_sel:[1,0,0]
	v_mov_b32_e32 v122, v133
	v_pk_fma_f32 v[44:45], v[132:133], v[78:79], v[44:45] op_sel_hi:[0,1,1]
	v_pk_fma_f32 v[42:43], v[122:123], v[2:3], v[42:43] op_sel_hi:[0,1,1]
	v_pk_add_f32 v[42:43], v[42:43], v[44:45]
	v_pk_mul_f32 v[44:45], v[50:51], v[46:47]
	s_nop 0
	v_pk_fma_f32 v[44:45], v[60:61], v[86:87], v[44:45] neg_lo:[0,0,1] neg_hi:[0,0,1]
	s_nop 0
	v_pk_add_f32 v[134:135], v[44:45], v[42:43]
	v_pk_mul_f32 v[44:45], v[50:51], v[86:87]
	v_bfe_u32 v41, v134, 16, 1
	v_pk_fma_f32 v[44:45], v[60:61], v[46:47], v[44:45]
	v_add3_u32 v41, v134, v41, s29
	v_pk_add_f32 v[46:47], v[44:45], v[42:43] op_sel:[0,1] op_sel_hi:[1,0]
	ds_write_b16_d16_hi v88, v41 offset:3536
	v_bfe_u32 v41, v46, 16, 1
	v_add3_u32 v41, v46, v41, s29
	ds_write_b16_d16_hi v88, v41 offset:3664
	ds_read_b128 v[42:45], v40 offset:960
	ds_read_b128 v[122:125], v40 offset:976
	ds_read_b128 v[126:129], v40 offset:992
	ds_read_b128 v[130:133], v40 offset:1008
	s_waitcnt lgkmcnt(9)
	v_pk_fma_f32 v[86:87], v[200:201], v[64:65], 0 op_sel_hi:[0,1,0]
	v_pk_fma_f32 v[200:201], v[200:201], v[12:13], 0 op_sel:[1,0,0] op_sel_hi:[1,1,0]
	v_pk_fma_f32 v[86:87], v[202:203], v[66:67], v[86:87] op_sel_hi:[0,1,1]
	v_mov_b32_e32 v202, v203
	v_pk_fma_f32 v[200:201], v[202:203], v[14:15], v[200:201] op_sel_hi:[0,1,1]
	s_waitcnt lgkmcnt(8)
	v_pk_fma_f32 v[202:203], v[204:205], v[68:69], v[86:87] op_sel_hi:[0,1,1]
	v_pk_fma_f32 v[200:201], v[204:205], v[8:9], v[200:201] op_sel:[1,0,0]
	v_mov_b32_e32 v86, v207
	v_pk_fma_f32 v[202:203], v[206:207], v[70:71], v[202:203] op_sel_hi:[0,1,1]
	v_pk_fma_f32 v[200:201], v[86:87], v[10:11], v[200:201] op_sel_hi:[0,1,1]
	s_waitcnt lgkmcnt(7)
	v_pk_fma_f32 v[202:203], v[208:209], v[72:73], v[202:203] op_sel_hi:[0,1,1]
	v_pk_fma_f32 v[200:201], v[208:209], v[4:5], v[200:201] op_sel:[1,0,0]
	v_mov_b32_e32 v86, v211
	v_pk_fma_f32 v[202:203], v[210:211], v[74:75], v[202:203] op_sel_hi:[0,1,1]
	v_pk_fma_f32 v[200:201], v[86:87], v[6:7], v[200:201] op_sel_hi:[0,1,1]
	s_waitcnt lgkmcnt(6)
	v_pk_fma_f32 v[202:203], v[212:213], v[76:77], v[202:203] op_sel_hi:[0,1,1]
	v_pk_fma_f32 v[200:201], v[212:213], v[0:1], v[200:201] op_sel:[1,0,0]
	v_mov_b32_e32 v86, v215
	v_pk_fma_f32 v[202:203], v[214:215], v[78:79], v[202:203] op_sel_hi:[0,1,1]
	v_pk_fma_f32 v[200:201], v[86:87], v[2:3], v[200:201] op_sel_hi:[0,1,1]
	v_pk_add_f32 v[200:201], v[200:201], v[202:203]
	v_pk_mul_f32 v[202:203], v[50:51], v[46:47]
	s_nop 0
	v_pk_fma_f32 v[202:203], v[60:61], v[134:135], v[202:203] neg_lo:[0,0,1] neg_hi:[0,0,1]
	s_nop 0
	v_pk_add_f32 v[86:87], v[202:203], v[200:201]
	v_pk_mul_f32 v[202:203], v[50:51], v[134:135]
	v_bfe_u32 v41, v86, 16, 1
	v_pk_fma_f32 v[202:203], v[60:61], v[46:47], v[202:203]
	v_add3_u32 v41, v86, v41, s29
	v_pk_add_f32 v[46:47], v[202:203], v[200:201] op_sel:[0,1] op_sel_hi:[1,0]
	ds_write_b16_d16_hi v88, v41 offset:3808
	v_bfe_u32 v41, v46, 16, 1
	v_add3_u32 v41, v46, v41, s29
	ds_write_b16_d16_hi v88, v41 offset:3936
	ds_read_b128 v[200:203], v40 offset:1024
	ds_read_b128 v[204:207], v40 offset:1040
	ds_read_b128 v[208:211], v40 offset:1056
	ds_read_b128 v[212:215], v40 offset:1072
	s_waitcnt lgkmcnt(9)
	v_pk_fma_f32 v[134:135], v[42:43], v[64:65], 0 op_sel_hi:[0,1,0]
	v_pk_fma_f32 v[42:43], v[42:43], v[12:13], 0 op_sel:[1,0,0] op_sel_hi:[1,1,0]
	v_pk_fma_f32 v[134:135], v[44:45], v[66:67], v[134:135] op_sel_hi:[0,1,1]
	v_mov_b32_e32 v44, v45
	v_pk_fma_f32 v[42:43], v[44:45], v[14:15], v[42:43] op_sel_hi:[0,1,1]
	s_waitcnt lgkmcnt(8)
	v_pk_fma_f32 v[44:45], v[122:123], v[68:69], v[134:135] op_sel_hi:[0,1,1]
	v_pk_fma_f32 v[42:43], v[122:123], v[8:9], v[42:43] op_sel:[1,0,0]
	v_mov_b32_e32 v122, v125
	v_pk_fma_f32 v[44:45], v[124:125], v[70:71], v[44:45] op_sel_hi:[0,1,1]
	v_pk_fma_f32 v[42:43], v[122:123], v[10:11], v[42:43] op_sel_hi:[0,1,1]
	s_waitcnt lgkmcnt(7)
	v_pk_fma_f32 v[44:45], v[126:127], v[72:73], v[44:45] op_sel_hi:[0,1,1]
	v_pk_fma_f32 v[42:43], v[126:127], v[4:5], v[42:43] op_sel:[1,0,0]
	v_mov_b32_e32 v122, v129
	v_pk_fma_f32 v[44:45], v[128:129], v[74:75], v[44:45] op_sel_hi:[0,1,1]
	v_pk_fma_f32 v[42:43], v[122:123], v[6:7], v[42:43] op_sel_hi:[0,1,1]
	s_waitcnt lgkmcnt(6)
; #define LAS __attribute__((address_space(3)))
; __device__ __forceinline__ unsigned f2bf(float f) { unsigned u = __builtin_bit_cast(unsigned, f); return (u + 0x7fffu + ((u >> 16) & 1u)) >> 16; }
; __device__ __forceinline__ void s5_phase(LAS unsigned char* lds, const unsigned char* ws, const bf16_t* proj, const float* c_re, const float* c_im, const float* dskip, bf16_t* z,
;                                          int vcu, int G, int wave, int lane) {
;     ...
;             for (int k = 0; k < 32; ++k) {
;                 f32x2 xa = (f32x2){0.f, 0.f}, xb = (f32x2){0.f, 0.f};
; #pragma unroll
;                 for (int q = 0; q < 4; ++q) { const f32x4 u4 = *(const LAS f32x4*)(Uc + k * 16 + 4 * q);
;                     xa = __builtin_elementwise_fma((f32x2){u4[0], u4[0]}, (f32x2){bbre[4 * q], bbim[4 * q]}, xa);
;                     xb = __builtin_elementwise_fma((f32x2){u4[1], u4[1]}, (f32x2){bbre[4 * q + 1], bbim[4 * q + 1]}, xb);
;                     xa = __builtin_elementwise_fma((f32x2){u4[2], u4[2]}, (f32x2){bbre[4 * q + 2], bbim[4 * q + 2]}, xa);
;                     xb = __builtin_elementwise_fma((f32x2){u4[3], u4[3]}, (f32x2){bbre[4 * q + 3], bbim[4 * q + 3]}, xb); }
;                 const f32x2 xx = xa + xb;
;                 const float nr = are * hre - aim * him + xx[0], ni = are * him + aim * hre + xx[1]; hre = nr; him = ni;
;                 Hc[k * 136 + n] = (bf16_t)f2bf(hre); Hc[k * 136 + 64 + n] = (bf16_t)f2bf(him);
;             }
	v_pk_fma_f32 v[44:45], v[130:131], v[76:77], v[44:45] op_sel_hi:[0,1,1]
	v_pk_fma_f32 v[42:43], v[130:131], v[0:1], v[42:43] op_sel:[1,0,0]
	v_mov_b32_e32 v122, v133
	v_pk_fma_f32 v[44:45], v[132:133], v[78:79], v[44:45] op_sel_hi:[0,1,1]
	v_pk_fma_f32 v[42:43], v[122:123], v[2:3], v[42:43] op_sel_hi:[0,1,1]
	v_pk_add_f32 v[42:43], v[42:43], v[44:45]
	v_pk_mul_f32 v[44:45], v[50:51], v[46:47]
	s_nop 0
	v_pk_fma_f32 v[44:45], v[60:61], v[86:87], v[44:45] neg_lo:[0,0,1] neg_hi:[0,0,1]
	s_nop 0
	v_pk_add_f32 v[134:135], v[44:45], v[42:43]
	v_pk_mul_f32 v[44:45], v[50:51], v[86:87]
	v_bfe_u32 v41, v134, 16, 1
	v_pk_fma_f32 v[44:45], v[60:61], v[46:47], v[44:45]
	v_add3_u32 v41, v134, v41, s29
	v_pk_add_f32 v[46:47], v[44:45], v[42:43] op_sel:[0,1] op_sel_hi:[1,0]
	ds_write_b16_d16_hi v88, v41 offset:4080
	v_bfe_u32 v41, v46, 16, 1
	v_add3_u32 v41, v46, v41, s29
	ds_write_b16_d16_hi v88, v41 offset:4208
	ds_read_b128 v[42:45], v40 offset:1088
	ds_read_b128 v[122:125], v40 offset:1104
	ds_read_b128 v[126:129], v40 offset:1120
	ds_read_b128 v[130:133], v40 offset:1136
	s_waitcnt lgkmcnt(9)
	v_pk_fma_f32 v[86:87], v[200:201], v[64:65], 0 op_sel_hi:[0,1,0]
	v_pk_fma_f32 v[200:201], v[200:201], v[12:13], 0 op_sel:[1,0,0] op_sel_hi:[1,1,0]
	v_pk_fma_f32 v[86:87], v[202:203], v[66:67], v[86:87] op_sel_hi:[0,1,1]
	v_mov_b32_e32 v202, v203
	v_pk_fma_f32 v[200:201], v[202:203], v[14:15], v[200:201] op_sel_hi:[0,1,1]
	s_waitcnt lgkmcnt(8)
	v_pk_fma_f32 v[202:203], v[204:205], v[68:69], v[86:87] op_sel_hi:[0,1,1]
	v_pk_fma_f32 v[200:201], v[204:205], v[8:9], v[200:201] op_sel:[1,0,0]
	v_mov_b32_e32 v86, v207
	v_pk_fma_f32 v[202:203], v[206:207], v[70:71], v[202:203] op_sel_hi:[0,1,1]
	v_pk_fma_f32 v[200:201], v[86:87], v[10:11], v[200:201] op_sel_hi:[0,1,1]
	s_waitcnt lgkmcnt(7)
	v_pk_fma_f32 v[202:203], v[208:209], v[72:73], v[202:203] op_sel_hi:[0,1,1]
	v_pk_fma_f32 v[200:201], v[208:209], v[4:5], v[200:201] op_sel:[1,0,0]
	v_mov_b32_e32 v86, v211
	v_pk_fma_f32 v[202:203], v[210:211], v[74:75], v[202:203] op_sel_hi:[0,1,1]
	v_pk_fma_f32 v[200:201], v[86:87], v[6:7], v[200:201] op_sel_hi:[0,1,1]
	s_waitcnt lgkmcnt(6)
	v_pk_fma_f32 v[202:203], v[212:213], v[76:77], v[202:203] op_sel_hi:[0,1,1]
	v_pk_fma_f32 v[200:201], v[212:213], v[0:1], v[200:201] op_sel:[1,0,0]
	v_mov_b32_e32 v86, v215
	v_pk_fma_f32 v[202:203], v[214:215], v[78:79], v[202:203] op_sel_hi:[0,1,1]
	v_pk_fma_f32 v[200:201], v[86:87], v[2:3], v[200:201] op_sel_hi:[0,1,1]
	v_pk_add_f32 v[200:201], v[200:201], v[202:203]
	v_pk_mul_f32 v[202:203], v[50:51], v[46:47]
	s_nop 0
	v_pk_fma_f32 v[202:203], v[60:61], v[134:135], v[202:203] neg_lo:[0,0,1] neg_hi:[0,0,1]
	s_nop 0
	v_pk_add_f32 v[86:87], v[202:203], v[200:201]
	v_pk_mul_f32 v[202:203], v[50:51], v[134:135]
	v_bfe_u32 v41, v86, 16, 1
	v_pk_fma_f32 v[202:203], v[60:61], v[46:47], v[202:203]
	v_add3_u32 v41, v86, v41, s29
	v_pk_add_f32 v[46:47], v[202:203], v[200:201] op_sel:[0,1] op_sel_hi:[1,0]
	ds_write_b16_d16_hi v88, v41 offset:4352
	v_bfe_u32 v41, v46, 16, 1
	v_add3_u32 v41, v46, v41, s29
	ds_write_b16_d16_hi v88, v41 offset:4480
	ds_read_b128 v[200:203], v40 offset:1152
	ds_read_b128 v[204:207], v40 offset:1168
	ds_read_b128 v[208:211], v40 offset:1184
	ds_read_b128 v[212:215], v40 offset:1200
	s_waitcnt lgkmcnt(9)
	v_pk_fma_f32 v[134:135], v[42:43], v[64:65], 0 op_sel_hi:[0,1,0]
	v_pk_fma_f32 v[42:43], v[42:43], v[12:13], 0 op_sel:[1,0,0] op_sel_hi:[1,1,0]
	v_pk_fma_f32 v[134:135], v[44:45], v[66:67], v[134:135] op_sel_hi:[0,1,1]
	v_mov_b32_e32 v44, v45
	v_pk_fma_f32 v[42:43], v[44:45], v[14:15], v[42:43] op_sel_hi:[0,1,1]
	s_waitcnt lgkmcnt(8)
	v_pk_fma_f32 v[44:45], v[122:123], v[68:69], v[134:135] op_sel_hi:[0,1,1]
	v_pk_fma_f32 v[42:43], v[122:123], v[8:9], v[42:43] op_sel:[1,0,0]
	v_mov_b32_e32 v122, v125
	v_pk_fma_f32 v[44:45], v[124:125], v[70:71], v[44:45] op_sel_hi:[0,1,1]
	v_pk_fma_f32 v[42:43], v[122:123], v[10:11], v[42:43] op_sel_hi:[0,1,1]
	s_waitcnt lgkmcnt(7)
	v_pk_fma_f32 v[44:45], v[126:127], v[72:73], v[44:45] op_sel_hi:[0,1,1]
	v_pk_fma_f32 v[42:43], v[126:127], v[4:5], v[42:43] op_sel:[1,0,0]
	v_mov_b32_e32 v122, v129
	v_pk_fma_f32 v[44:45], v[128:129], v[74:75], v[44:45] op_sel_hi:[0,1,1]
	v_pk_fma_f32 v[42:43], v[122:123], v[6:7], v[42:43] op_sel_hi:[0,1,1]
	s_waitcnt lgkmcnt(6)
	v_pk_fma_f32 v[44:45], v[130:131], v[76:77], v[44:45] op_sel_hi:[0,1,1]
	v_pk_fma_f32 v[42:43], v[130:131], v[0:1], v[42:43] op_sel:[1,0,0]
	v_mov_b32_e32 v122, v133
	v_pk_fma_f32 v[44:45], v[132:133], v[78:79], v[44:45] op_sel_hi:[0,1,1]
	v_pk_fma_f32 v[42:43], v[122:123], v[2:3], v[42:43] op_sel_hi:[0,1,1]
	v_pk_add_f32 v[42:43], v[42:43], v[44:45]
	v_pk_mul_f32 v[44:45], v[50:51], v[46:47]
	s_nop 0
	v_pk_fma_f32 v[44:45], v[60:61], v[86:87], v[44:45] neg_lo:[0,0,1] neg_hi:[0,0,1]
	s_nop 0
	v_pk_add_f32 v[134:135], v[44:45], v[42:43]
	v_pk_mul_f32 v[44:45], v[50:51], v[86:87]
	v_bfe_u32 v41, v134, 16, 1
	v_pk_fma_f32 v[44:45], v[60:61], v[46:47], v[44:45]
	v_add3_u32 v41, v134, v41, s29
	v_pk_add_f32 v[46:47], v[44:45], v[42:43] op_sel:[0,1] op_sel_hi:[1,0]
	ds_write_b16_d16_hi v88, v41 offset:4624
	v_bfe_u32 v41, v46, 16, 1
	v_add3_u32 v41, v46, v41, s29
	ds_write_b16_d16_hi v88, v41 offset:4752
	ds_read_b128 v[42:45], v40 offset:1216
	ds_read_b128 v[122:125], v40 offset:1232
	ds_read_b128 v[126:129], v40 offset:1248
	ds_read_b128 v[130:133], v40 offset:1264
	s_waitcnt lgkmcnt(9)
	v_pk_fma_f32 v[86:87], v[200:201], v[64:65], 0 op_sel_hi:[0,1,0]
	v_pk_fma_f32 v[200:201], v[200:201], v[12:13], 0 op_sel:[1,0,0] op_sel_hi:[1,1,0]
	v_pk_fma_f32 v[86:87], v[202:203], v[66:67], v[86:87] op_sel_hi:[0,1,1]
	v_mov_b32_e32 v202, v203
	v_pk_fma_f32 v[200:201], v[202:203], v[14:15], v[200:201] op_sel_hi:[0,1,1]
	s_waitcnt lgkmcnt(8)
; #define LAS __attribute__((address_space(3)))
; __device__ __forceinline__ unsigned f2bf(float f) { unsigned u = __builtin_bit_cast(unsigned, f); return (u + 0x7fffu + ((u >> 16) & 1u)) >> 16; }
; __device__ __forceinline__ void s5_phase(LAS unsigned char* lds, const unsigned char* ws, const bf16_t* proj, const float* c_re, const float* c_im, const float* dskip, bf16_t* z,
;                                          int vcu, int G, int wave, int lane) {
;     ...
;             for (int k = 0; k < 32; ++k) {
;                 f32x2 xa = (f32x2){0.f, 0.f}, xb = (f32x2){0.f, 0.f};
; #pragma unroll
;                 for (int q = 0; q < 4; ++q) { const f32x4 u4 = *(const LAS f32x4*)(Uc + k * 16 + 4 * q);
;                     xa = __builtin_elementwise_fma((f32x2){u4[0], u4[0]}, (f32x2){bbre[4 * q], bbim[4 * q]}, xa);
;                     xb = __builtin_elementwise_fma((f32x2){u4[1], u4[1]}, (f32x2){bbre[4 * q + 1], bbim[4 * q + 1]}, xb);
;                     xa = __builtin_elementwise_fma((f32x2){u4[2], u4[2]}, (f32x2){bbre[4 * q + 2], bbim[4 * q + 2]}, xa);
;                     xb = __builtin_elementwise_fma((f32x2){u4[3], u4[3]}, (f32x2){bbre[4 * q + 3], bbim[4 * q + 3]}, xb); }
;                 const f32x2 xx = xa + xb;
;                 const float nr = are * hre - aim * him + xx[0], ni = are * him + aim * hre + xx[1]; hre = nr; him = ni;
;                 Hc[k * 136 + n] = (bf16_t)f2bf(hre); Hc[k * 136 + 64 + n] = (bf16_t)f2bf(him);
;             }
	v_pk_fma_f32 v[202:203], v[204:205], v[68:69], v[86:87] op_sel_hi:[0,1,1]
	v_pk_fma_f32 v[200:201], v[204:205], v[8:9], v[200:201] op_sel:[1,0,0]
	v_mov_b32_e32 v86, v207
	v_pk_fma_f32 v[202:203], v[206:207], v[70:71], v[202:203] op_sel_hi:[0,1,1]
	v_pk_fma_f32 v[200:201], v[86:87], v[10:11], v[200:201] op_sel_hi:[0,1,1]
	s_waitcnt lgkmcnt(7)
	v_pk_fma_f32 v[202:203], v[208:209], v[72:73], v[202:203] op_sel_hi:[0,1,1]
	v_pk_fma_f32 v[200:201], v[208:209], v[4:5], v[200:201] op_sel:[1,0,0]
	v_mov_b32_e32 v86, v211
	v_pk_fma_f32 v[202:203], v[210:211], v[74:75], v[202:203] op_sel_hi:[0,1,1]
	v_pk_fma_f32 v[200:201], v[86:87], v[6:7], v[200:201] op_sel_hi:[0,1,1]
	s_waitcnt lgkmcnt(6)
	v_pk_fma_f32 v[202:203], v[212:213], v[76:77], v[202:203] op_sel_hi:[0,1,1]
	v_pk_fma_f32 v[200:201], v[212:213], v[0:1], v[200:201] op_sel:[1,0,0]
	v_mov_b32_e32 v86, v215
	v_pk_fma_f32 v[202:203], v[214:215], v[78:79], v[202:203] op_sel_hi:[0,1,1]
	v_pk_fma_f32 v[200:201], v[86:87], v[2:3], v[200:201] op_sel_hi:[0,1,1]
	v_pk_add_f32 v[200:201], v[200:201], v[202:203]
	v_pk_mul_f32 v[202:203], v[50:51], v[46:47]
	s_nop 0
	v_pk_fma_f32 v[202:203], v[60:61], v[134:135], v[202:203] neg_lo:[0,0,1] neg_hi:[0,0,1]
	s_nop 0
	v_pk_add_f32 v[86:87], v[202:203], v[200:201]
	v_pk_mul_f32 v[202:203], v[50:51], v[134:135]
	v_bfe_u32 v41, v86, 16, 1
	v_pk_fma_f32 v[202:203], v[60:61], v[46:47], v[202:203]
	v_add3_u32 v41, v86, v41, s29
	v_pk_add_f32 v[46:47], v[202:203], v[200:201] op_sel:[0,1] op_sel_hi:[1,0]
	ds_write_b16_d16_hi v88, v41 offset:4896
	v_bfe_u32 v41, v46, 16, 1
	v_add3_u32 v41, v46, v41, s29
	ds_write_b16_d16_hi v88, v41 offset:5024
	ds_read_b128 v[200:203], v40 offset:1280
	ds_read_b128 v[204:207], v40 offset:1296
	ds_read_b128 v[208:211], v40 offset:1312
	ds_read_b128 v[212:215], v40 offset:1328
	s_waitcnt lgkmcnt(9)
	v_pk_fma_f32 v[134:135], v[42:43], v[64:65], 0 op_sel_hi:[0,1,0]
	v_pk_fma_f32 v[42:43], v[42:43], v[12:13], 0 op_sel:[1,0,0] op_sel_hi:[1,1,0]
	v_pk_fma_f32 v[134:135], v[44:45], v[66:67], v[134:135] op_sel_hi:[0,1,1]
	v_mov_b32_e32 v44, v45
	v_pk_fma_f32 v[42:43], v[44:45], v[14:15], v[42:43] op_sel_hi:[0,1,1]
	s_waitcnt lgkmcnt(8)
	v_pk_fma_f32 v[44:45], v[122:123], v[68:69], v[134:135] op_sel_hi:[0,1,1]
	v_pk_fma_f32 v[42:43], v[122:123], v[8:9], v[42:43] op_sel:[1,0,0]
	v_mov_b32_e32 v122, v125
	v_pk_fma_f32 v[44:45], v[124:125], v[70:71], v[44:45] op_sel_hi:[0,1,1]
	v_pk_fma_f32 v[42:43], v[122:123], v[10:11], v[42:43] op_sel_hi:[0,1,1]
	s_waitcnt lgkmcnt(7)
	v_pk_fma_f32 v[44:45], v[126:127], v[72:73], v[44:45] op_sel_hi:[0,1,1]
	v_pk_fma_f32 v[42:43], v[126:127], v[4:5], v[42:43] op_sel:[1,0,0]
	v_mov_b32_e32 v122, v129
	v_pk_fma_f32 v[44:45], v[128:129], v[74:75], v[44:45] op_sel_hi:[0,1,1]
	v_pk_fma_f32 v[42:43], v[122:123], v[6:7], v[42:43] op_sel_hi:[0,1,1]
	s_waitcnt lgkmcnt(6)
	v_pk_fma_f32 v[44:45], v[130:131], v[76:77], v[44:45] op_sel_hi:[0,1,1]
	v_pk_fma_f32 v[42:43], v[130:131], v[0:1], v[42:43] op_sel:[1,0,0]
	v_mov_b32_e32 v122, v133
	v_pk_fma_f32 v[44:45], v[132:133], v[78:79], v[44:45] op_sel_hi:[0,1,1]
	v_pk_fma_f32 v[42:43], v[122:123], v[2:3], v[42:43] op_sel_hi:[0,1,1]
	v_pk_add_f32 v[42:43], v[42:43], v[44:45]
	v_pk_mul_f32 v[44:45], v[50:51], v[46:47]
	s_nop 0
	v_pk_fma_f32 v[44:45], v[60:61], v[86:87], v[44:45] neg_lo:[0,0,1] neg_hi:[0,0,1]
	s_nop 0
	v_pk_add_f32 v[134:135], v[44:45], v[42:43]
	v_pk_mul_f32 v[44:45], v[50:51], v[86:87]
	v_bfe_u32 v41, v134, 16, 1
	v_pk_fma_f32 v[44:45], v[60:61], v[46:47], v[44:45]
	v_add3_u32 v41, v134, v41, s29
	v_pk_add_f32 v[46:47], v[44:45], v[42:43] op_sel:[0,1] op_sel_hi:[1,0]
	ds_write_b16_d16_hi v88, v41 offset:5168
	v_bfe_u32 v41, v46, 16, 1
	v_add3_u32 v41, v46, v41, s29
	ds_write_b16_d16_hi v88, v41 offset:5296
	ds_read_b128 v[42:45], v40 offset:1344
	ds_read_b128 v[122:125], v40 offset:1360
	ds_read_b128 v[126:129], v40 offset:1376
	ds_read_b128 v[130:133], v40 offset:1392
	s_waitcnt lgkmcnt(9)
	v_pk_fma_f32 v[86:87], v[200:201], v[64:65], 0 op_sel_hi:[0,1,0]
	v_pk_fma_f32 v[200:201], v[200:201], v[12:13], 0 op_sel:[1,0,0] op_sel_hi:[1,1,0]
	v_pk_fma_f32 v[86:87], v[202:203], v[66:67], v[86:87] op_sel_hi:[0,1,1]
	v_mov_b32_e32 v202, v203
	v_pk_fma_f32 v[200:201], v[202:203], v[14:15], v[200:201] op_sel_hi:[0,1,1]
	s_waitcnt lgkmcnt(8)
	v_pk_fma_f32 v[202:203], v[204:205], v[68:69], v[86:87] op_sel_hi:[0,1,1]
	v_pk_fma_f32 v[200:201], v[204:205], v[8:9], v[200:201] op_sel:[1,0,0]
	v_mov_b32_e32 v86, v207
	v_pk_fma_f32 v[202:203], v[206:207], v[70:71], v[202:203] op_sel_hi:[0,1,1]
	v_pk_fma_f32 v[200:201], v[86:87], v[10:11], v[200:201] op_sel_hi:[0,1,1]
	s_waitcnt lgkmcnt(7)
	v_pk_fma_f32 v[202:203], v[208:209], v[72:73], v[202:203] op_sel_hi:[0,1,1]
	v_pk_fma_f32 v[200:201], v[208:209], v[4:5], v[200:201] op_sel:[1,0,0]
	v_mov_b32_e32 v86, v211
	v_pk_fma_f32 v[202:203], v[210:211], v[74:75], v[202:203] op_sel_hi:[0,1,1]
	v_pk_fma_f32 v[200:201], v[86:87], v[6:7], v[200:201] op_sel_hi:[0,1,1]
	s_waitcnt lgkmcnt(6)
	v_pk_fma_f32 v[202:203], v[212:213], v[76:77], v[202:203] op_sel_hi:[0,1,1]
	v_pk_fma_f32 v[200:201], v[212:213], v[0:1], v[200:201] op_sel:[1,0,0]
	v_mov_b32_e32 v86, v215
	v_pk_fma_f32 v[202:203], v[214:215], v[78:79], v[202:203] op_sel_hi:[0,1,1]
	v_pk_fma_f32 v[200:201], v[86:87], v[2:3], v[200:201] op_sel_hi:[0,1,1]
	v_pk_add_f32 v[200:201], v[200:201], v[202:203]
	v_pk_mul_f32 v[202:203], v[50:51], v[46:47]
	s_nop 0
	v_pk_fma_f32 v[202:203], v[60:61], v[134:135], v[202:203] neg_lo:[0,0,1] neg_hi:[0,0,1]
	s_nop 0
	v_pk_add_f32 v[86:87], v[202:203], v[200:201]
	v_pk_mul_f32 v[202:203], v[50:51], v[134:135]
	v_bfe_u32 v41, v86, 16, 1
	v_pk_fma_f32 v[202:203], v[60:61], v[46:47], v[202:203]
	v_add3_u32 v41, v86, v41, s29
	v_pk_add_f32 v[46:47], v[202:203], v[200:201] op_sel:[0,1] op_sel_hi:[1,0]
	ds_write_b16_d16_hi v88, v41 offset:5440
	v_bfe_u32 v41, v46, 16, 1
	v_add3_u32 v41, v46, v41, s29
	ds_write_b16_d16_hi v88, v41 offset:5568
	ds_read_b128 v[200:203], v40 offset:1408
	ds_read_b128 v[204:207], v40 offset:1424
	ds_read_b128 v[208:211], v40 offset:1440
	ds_read_b128 v[212:215], v40 offset:1456
	s_waitcnt lgkmcnt(9)
; #define LAS __attribute__((address_space(3)))
; __device__ __forceinline__ unsigned f2bf(float f) { unsigned u = __builtin_bit_cast(unsigned, f); return (u + 0x7fffu + ((u >> 16) & 1u)) >> 16; }
; __device__ __forceinline__ void s5_phase(LAS unsigned char* lds, const unsigned char* ws, const bf16_t* proj, const float* c_re, const float* c_im, const float* dskip, bf16_t* z,
;                                          int vcu, int G, int wave, int lane) {
;     ...
;             for (int k = 0; k < 32; ++k) {
;                 f32x2 xa = (f32x2){0.f, 0.f}, xb = (f32x2){0.f, 0.f};
; #pragma unroll
;                 for (int q = 0; q < 4; ++q) { const f32x4 u4 = *(const LAS f32x4*)(Uc + k * 16 + 4 * q);
;                     xa = __builtin_elementwise_fma((f32x2){u4[0], u4[0]}, (f32x2){bbre[4 * q], bbim[4 * q]}, xa);
;                     xb = __builtin_elementwise_fma((f32x2){u4[1], u4[1]}, (f32x2){bbre[4 * q + 1], bbim[4 * q + 1]}, xb);
;                     xa = __builtin_elementwise_fma((f32x2){u4[2], u4[2]}, (f32x2){bbre[4 * q + 2], bbim[4 * q + 2]}, xa);
;                     xb = __builtin_elementwise_fma((f32x2){u4[3], u4[3]}, (f32x2){bbre[4 * q + 3], bbim[4 * q + 3]}, xb); }
;                 const f32x2 xx = xa + xb;
;                 const float nr = are * hre - aim * him + xx[0], ni = are * him + aim * hre + xx[1]; hre = nr; him = ni;
;                 Hc[k * 136 + n] = (bf16_t)f2bf(hre); Hc[k * 136 + 64 + n] = (bf16_t)f2bf(him);
;             }
	v_pk_fma_f32 v[134:135], v[42:43], v[64:65], 0 op_sel_hi:[0,1,0]
	v_pk_fma_f32 v[42:43], v[42:43], v[12:13], 0 op_sel:[1,0,0] op_sel_hi:[1,1,0]
	v_pk_fma_f32 v[134:135], v[44:45], v[66:67], v[134:135] op_sel_hi:[0,1,1]
	v_mov_b32_e32 v44, v45
	v_pk_fma_f32 v[42:43], v[44:45], v[14:15], v[42:43] op_sel_hi:[0,1,1]
	s_waitcnt lgkmcnt(8)
	v_pk_fma_f32 v[44:45], v[122:123], v[68:69], v[134:135] op_sel_hi:[0,1,1]
	v_pk_fma_f32 v[42:43], v[122:123], v[8:9], v[42:43] op_sel:[1,0,0]
	v_mov_b32_e32 v122, v125
	v_pk_fma_f32 v[44:45], v[124:125], v[70:71], v[44:45] op_sel_hi:[0,1,1]
	v_pk_fma_f32 v[42:43], v[122:123], v[10:11], v[42:43] op_sel_hi:[0,1,1]
	s_waitcnt lgkmcnt(7)
	v_pk_fma_f32 v[44:45], v[126:127], v[72:73], v[44:45] op_sel_hi:[0,1,1]
	v_pk_fma_f32 v[42:43], v[126:127], v[4:5], v[42:43] op_sel:[1,0,0]
	v_mov_b32_e32 v122, v129
	v_pk_fma_f32 v[44:45], v[128:129], v[74:75], v[44:45] op_sel_hi:[0,1,1]
	v_pk_fma_f32 v[42:43], v[122:123], v[6:7], v[42:43] op_sel_hi:[0,1,1]
	s_waitcnt lgkmcnt(6)
	v_pk_fma_f32 v[44:45], v[130:131], v[76:77], v[44:45] op_sel_hi:[0,1,1]
	v_pk_fma_f32 v[42:43], v[130:131], v[0:1], v[42:43] op_sel:[1,0,0]
	v_mov_b32_e32 v122, v133
	v_pk_fma_f32 v[44:45], v[132:133], v[78:79], v[44:45] op_sel_hi:[0,1,1]
	v_pk_fma_f32 v[42:43], v[122:123], v[2:3], v[42:43] op_sel_hi:[0,1,1]
	v_pk_add_f32 v[42:43], v[42:43], v[44:45]
	v_pk_mul_f32 v[44:45], v[50:51], v[46:47]
	s_nop 0
	v_pk_fma_f32 v[44:45], v[60:61], v[86:87], v[44:45] neg_lo:[0,0,1] neg_hi:[0,0,1]
	s_nop 0
	v_pk_add_f32 v[134:135], v[44:45], v[42:43]
	v_pk_mul_f32 v[44:45], v[50:51], v[86:87]
	v_bfe_u32 v41, v134, 16, 1
	v_pk_fma_f32 v[44:45], v[60:61], v[46:47], v[44:45]
	v_add3_u32 v41, v134, v41, s29
	v_pk_add_f32 v[46:47], v[44:45], v[42:43] op_sel:[0,1] op_sel_hi:[1,0]
	ds_write_b16_d16_hi v88, v41 offset:5712
	v_bfe_u32 v41, v46, 16, 1
	v_add3_u32 v41, v46, v41, s29
	ds_write_b16_d16_hi v88, v41 offset:5840
	ds_read_b128 v[42:45], v40 offset:1472
	ds_read_b128 v[122:125], v40 offset:1488
	ds_read_b128 v[126:129], v40 offset:1504
	ds_read_b128 v[130:133], v40 offset:1520
	s_waitcnt lgkmcnt(9)
	v_pk_fma_f32 v[86:87], v[200:201], v[64:65], 0 op_sel_hi:[0,1,0]
	v_pk_fma_f32 v[200:201], v[200:201], v[12:13], 0 op_sel:[1,0,0] op_sel_hi:[1,1,0]
	v_pk_fma_f32 v[86:87], v[202:203], v[66:67], v[86:87] op_sel_hi:[0,1,1]
	v_mov_b32_e32 v202, v203
	v_pk_fma_f32 v[200:201], v[202:203], v[14:15], v[200:201] op_sel_hi:[0,1,1]
	s_waitcnt lgkmcnt(8)
	v_pk_fma_f32 v[202:203], v[204:205], v[68:69], v[86:87] op_sel_hi:[0,1,1]
	v_pk_fma_f32 v[200:201], v[204:205], v[8:9], v[200:201] op_sel:[1,0,0]
	v_mov_b32_e32 v86, v207
	v_pk_fma_f32 v[202:203], v[206:207], v[70:71], v[202:203] op_sel_hi:[0,1,1]
	v_pk_fma_f32 v[200:201], v[86:87], v[10:11], v[200:201] op_sel_hi:[0,1,1]
	s_waitcnt lgkmcnt(7)
	v_pk_fma_f32 v[202:203], v[208:209], v[72:73], v[202:203] op_sel_hi:[0,1,1]
	v_pk_fma_f32 v[200:201], v[208:209], v[4:5], v[200:201] op_sel:[1,0,0]
	v_mov_b32_e32 v86, v211
	v_pk_fma_f32 v[202:203], v[210:211], v[74:75], v[202:203] op_sel_hi:[0,1,1]
	v_pk_fma_f32 v[200:201], v[86:87], v[6:7], v[200:201] op_sel_hi:[0,1,1]
	s_waitcnt lgkmcnt(6)
	v_pk_fma_f32 v[202:203], v[212:213], v[76:77], v[202:203] op_sel_hi:[0,1,1]
	v_pk_fma_f32 v[200:201], v[212:213], v[0:1], v[200:201] op_sel:[1,0,0]
	v_mov_b32_e32 v86, v215
	v_pk_fma_f32 v[202:203], v[214:215], v[78:79], v[202:203] op_sel_hi:[0,1,1]
	v_pk_fma_f32 v[200:201], v[86:87], v[2:3], v[200:201] op_sel_hi:[0,1,1]
	v_pk_add_f32 v[200:201], v[200:201], v[202:203]
	v_pk_mul_f32 v[202:203], v[50:51], v[46:47]
	s_nop 0
	v_pk_fma_f32 v[202:203], v[60:61], v[134:135], v[202:203] neg_lo:[0,0,1] neg_hi:[0,0,1]
	s_nop 0
	v_pk_add_f32 v[86:87], v[202:203], v[200:201]
	v_pk_mul_f32 v[202:203], v[50:51], v[134:135]
	v_bfe_u32 v41, v86, 16, 1
	v_pk_fma_f32 v[202:203], v[60:61], v[46:47], v[202:203]
	v_add3_u32 v41, v86, v41, s29
	v_pk_add_f32 v[46:47], v[202:203], v[200:201] op_sel:[0,1] op_sel_hi:[1,0]
	ds_write_b16_d16_hi v88, v41 offset:5984
	v_bfe_u32 v41, v46, 16, 1
	v_add3_u32 v41, v46, v41, s29
	ds_write_b16_d16_hi v88, v41 offset:6112
	ds_read_b128 v[200:203], v40 offset:1536
	ds_read_b128 v[204:207], v40 offset:1552
	ds_read_b128 v[208:211], v40 offset:1568
	ds_read_b128 v[212:215], v40 offset:1584
	s_waitcnt lgkmcnt(9)
	v_pk_fma_f32 v[134:135], v[42:43], v[64:65], 0 op_sel_hi:[0,1,0]
	v_pk_fma_f32 v[42:43], v[42:43], v[12:13], 0 op_sel:[1,0,0] op_sel_hi:[1,1,0]
	v_pk_fma_f32 v[134:135], v[44:45], v[66:67], v[134:135] op_sel_hi:[0,1,1]
	v_mov_b32_e32 v44, v45
	v_pk_fma_f32 v[42:43], v[44:45], v[14:15], v[42:43] op_sel_hi:[0,1,1]
	s_waitcnt lgkmcnt(8)
	v_pk_fma_f32 v[44:45], v[122:123], v[68:69], v[134:135] op_sel_hi:[0,1,1]
	v_pk_fma_f32 v[42:43], v[122:123], v[8:9], v[42:43] op_sel:[1,0,0]
	v_mov_b32_e32 v122, v125
	v_pk_fma_f32 v[44:45], v[124:125], v[70:71], v[44:45] op_sel_hi:[0,1,1]
	v_pk_fma_f32 v[42:43], v[122:123], v[10:11], v[42:43] op_sel_hi:[0,1,1]
	s_waitcnt lgkmcnt(7)
	v_pk_fma_f32 v[44:45], v[126:127], v[72:73], v[44:45] op_sel_hi:[0,1,1]
	v_pk_fma_f32 v[42:43], v[126:127], v[4:5], v[42:43] op_sel:[1,0,0]
	v_mov_b32_e32 v122, v129
	v_pk_fma_f32 v[44:45], v[128:129], v[74:75], v[44:45] op_sel_hi:[0,1,1]
	v_pk_fma_f32 v[42:43], v[122:123], v[6:7], v[42:43] op_sel_hi:[0,1,1]
	s_waitcnt lgkmcnt(6)
; #define LAS __attribute__((address_space(3)))
; __device__ __forceinline__ unsigned f2bf(float f) { unsigned u = __builtin_bit_cast(unsigned, f); return (u + 0x7fffu + ((u >> 16) & 1u)) >> 16; }
; __device__ __forceinline__ void s5_phase(LAS unsigned char* lds, const unsigned char* ws, const bf16_t* proj, const float* c_re, const float* c_im, const float* dskip, bf16_t* z,
;                                          int vcu, int G, int wave, int lane) {
;     ...
;             for (int k = 0; k < 32; ++k) {
;                 f32x2 xa = (f32x2){0.f, 0.f}, xb = (f32x2){0.f, 0.f};
; #pragma unroll
;                 for (int q = 0; q < 4; ++q) { const f32x4 u4 = *(const LAS f32x4*)(Uc + k * 16 + 4 * q);
;                     xa = __builtin_elementwise_fma((f32x2){u4[0], u4[0]}, (f32x2){bbre[4 * q], bbim[4 * q]}, xa);
;                     xb = __builtin_elementwise_fma((f32x2){u4[1], u4[1]}, (f32x2){bbre[4 * q + 1], bbim[4 * q + 1]}, xb);
;                     xa = __builtin_elementwise_fma((f32x2){u4[2], u4[2]}, (f32x2){bbre[4 * q + 2], bbim[4 * q + 2]}, xa);
;                     xb = __builtin_elementwise_fma((f32x2){u4[3], u4[3]}, (f32x2){bbre[4 * q + 3], bbim[4 * q + 3]}, xb); }
;                 const f32x2 xx = xa + xb;
;                 const float nr = are * hre - aim * him + xx[0], ni = are * him + aim * hre + xx[1]; hre = nr; him = ni;
;                 Hc[k * 136 + n] = (bf16_t)f2bf(hre); Hc[k * 136 + 64 + n] = (bf16_t)f2bf(him);
;             }
	v_pk_fma_f32 v[44:45], v[130:131], v[76:77], v[44:45] op_sel_hi:[0,1,1]
	v_pk_fma_f32 v[42:43], v[130:131], v[0:1], v[42:43] op_sel:[1,0,0]
	v_mov_b32_e32 v122, v133
	v_pk_fma_f32 v[44:45], v[132:133], v[78:79], v[44:45] op_sel_hi:[0,1,1]
	v_pk_fma_f32 v[42:43], v[122:123], v[2:3], v[42:43] op_sel_hi:[0,1,1]
	v_pk_add_f32 v[42:43], v[42:43], v[44:45]
	v_pk_mul_f32 v[44:45], v[50:51], v[46:47]
	s_nop 0
	v_pk_fma_f32 v[44:45], v[60:61], v[86:87], v[44:45] neg_lo:[0,0,1] neg_hi:[0,0,1]
	s_nop 0
	v_pk_add_f32 v[134:135], v[44:45], v[42:43]
	v_pk_mul_f32 v[44:45], v[50:51], v[86:87]
	v_bfe_u32 v41, v134, 16, 1
	v_pk_fma_f32 v[44:45], v[60:61], v[46:47], v[44:45]
	v_add3_u32 v41, v134, v41, s29
	v_pk_add_f32 v[46:47], v[44:45], v[42:43] op_sel:[0,1] op_sel_hi:[1,0]
	ds_write_b16_d16_hi v88, v41 offset:6256
	v_bfe_u32 v41, v46, 16, 1
	v_add3_u32 v41, v46, v41, s29
	ds_write_b16_d16_hi v88, v41 offset:6384
	ds_read_b128 v[42:45], v40 offset:1600
	ds_read_b128 v[122:125], v40 offset:1616
	ds_read_b128 v[126:129], v40 offset:1632
	ds_read_b128 v[130:133], v40 offset:1648
	s_waitcnt lgkmcnt(9)
	v_pk_fma_f32 v[86:87], v[200:201], v[64:65], 0 op_sel_hi:[0,1,0]
	v_pk_fma_f32 v[200:201], v[200:201], v[12:13], 0 op_sel:[1,0,0] op_sel_hi:[1,1,0]
	v_pk_fma_f32 v[86:87], v[202:203], v[66:67], v[86:87] op_sel_hi:[0,1,1]
	v_mov_b32_e32 v202, v203
	v_pk_fma_f32 v[200:201], v[202:203], v[14:15], v[200:201] op_sel_hi:[0,1,1]
	s_waitcnt lgkmcnt(8)
	v_pk_fma_f32 v[202:203], v[204:205], v[68:69], v[86:87] op_sel_hi:[0,1,1]
	v_pk_fma_f32 v[200:201], v[204:205], v[8:9], v[200:201] op_sel:[1,0,0]
	v_mov_b32_e32 v86, v207
	v_pk_fma_f32 v[202:203], v[206:207], v[70:71], v[202:203] op_sel_hi:[0,1,1]
	v_pk_fma_f32 v[200:201], v[86:87], v[10:11], v[200:201] op_sel_hi:[0,1,1]
	s_waitcnt lgkmcnt(7)
	v_pk_fma_f32 v[202:203], v[208:209], v[72:73], v[202:203] op_sel_hi:[0,1,1]
	v_pk_fma_f32 v[200:201], v[208:209], v[4:5], v[200:201] op_sel:[1,0,0]
	v_mov_b32_e32 v86, v211
	v_pk_fma_f32 v[202:203], v[210:211], v[74:75], v[202:203] op_sel_hi:[0,1,1]
	v_pk_fma_f32 v[200:201], v[86:87], v[6:7], v[200:201] op_sel_hi:[0,1,1]
	s_waitcnt lgkmcnt(6)
	v_pk_fma_f32 v[202:203], v[212:213], v[76:77], v[202:203] op_sel_hi:[0,1,1]
	v_pk_fma_f32 v[200:201], v[212:213], v[0:1], v[200:201] op_sel:[1,0,0]
	v_mov_b32_e32 v86, v215
	v_pk_fma_f32 v[202:203], v[214:215], v[78:79], v[202:203] op_sel_hi:[0,1,1]
	v_pk_fma_f32 v[200:201], v[86:87], v[2:3], v[200:201] op_sel_hi:[0,1,1]
	v_pk_add_f32 v[200:201], v[200:201], v[202:203]
	v_pk_mul_f32 v[202:203], v[50:51], v[46:47]
	s_nop 0
	v_pk_fma_f32 v[202:203], v[60:61], v[134:135], v[202:203] neg_lo:[0,0,1] neg_hi:[0,0,1]
	s_nop 0
	v_pk_add_f32 v[86:87], v[202:203], v[200:201]
	v_pk_mul_f32 v[202:203], v[50:51], v[134:135]
	v_bfe_u32 v41, v86, 16, 1
	v_pk_fma_f32 v[202:203], v[60:61], v[46:47], v[202:203]
	v_add3_u32 v41, v86, v41, s29
	v_pk_add_f32 v[46:47], v[202:203], v[200:201] op_sel:[0,1] op_sel_hi:[1,0]
	ds_write_b16_d16_hi v88, v41 offset:6528
	v_bfe_u32 v41, v46, 16, 1
	v_add3_u32 v41, v46, v41, s29
	ds_write_b16_d16_hi v88, v41 offset:6656
	ds_read_b128 v[200:203], v40 offset:1664
	ds_read_b128 v[204:207], v40 offset:1680
	ds_read_b128 v[208:211], v40 offset:1696
	ds_read_b128 v[212:215], v40 offset:1712
	s_waitcnt lgkmcnt(9)
	v_pk_fma_f32 v[134:135], v[42:43], v[64:65], 0 op_sel_hi:[0,1,0]
	v_pk_fma_f32 v[42:43], v[42:43], v[12:13], 0 op_sel:[1,0,0] op_sel_hi:[1,1,0]
	v_pk_fma_f32 v[134:135], v[44:45], v[66:67], v[134:135] op_sel_hi:[0,1,1]
	v_mov_b32_e32 v44, v45
	v_pk_fma_f32 v[42:43], v[44:45], v[14:15], v[42:43] op_sel_hi:[0,1,1]
	s_waitcnt lgkmcnt(8)
	v_pk_fma_f32 v[44:45], v[122:123], v[68:69], v[134:135] op_sel_hi:[0,1,1]
	v_pk_fma_f32 v[42:43], v[122:123], v[8:9], v[42:43] op_sel:[1,0,0]
	v_mov_b32_e32 v122, v125
	v_pk_fma_f32 v[44:45], v[124:125], v[70:71], v[44:45] op_sel_hi:[0,1,1]
	v_pk_fma_f32 v[42:43], v[122:123], v[10:11], v[42:43] op_sel_hi:[0,1,1]
	s_waitcnt lgkmcnt(7)
	v_pk_fma_f32 v[44:45], v[126:127], v[72:73], v[44:45] op_sel_hi:[0,1,1]
	v_pk_fma_f32 v[42:43], v[126:127], v[4:5], v[42:43] op_sel:[1,0,0]
	v_mov_b32_e32 v122, v129
	v_pk_fma_f32 v[44:45], v[128:129], v[74:75], v[44:45] op_sel_hi:[0,1,1]
	v_pk_fma_f32 v[42:43], v[122:123], v[6:7], v[42:43] op_sel_hi:[0,1,1]
	s_waitcnt lgkmcnt(6)
	v_pk_fma_f32 v[44:45], v[130:131], v[76:77], v[44:45] op_sel_hi:[0,1,1]
	v_pk_fma_f32 v[42:43], v[130:131], v[0:1], v[42:43] op_sel:[1,0,0]
	v_mov_b32_e32 v122, v133
	v_pk_fma_f32 v[44:45], v[132:133], v[78:79], v[44:45] op_sel_hi:[0,1,1]
	v_pk_fma_f32 v[42:43], v[122:123], v[2:3], v[42:43] op_sel_hi:[0,1,1]
	v_pk_add_f32 v[42:43], v[42:43], v[44:45]
	v_pk_mul_f32 v[44:45], v[50:51], v[46:47]
	s_nop 0
	v_pk_fma_f32 v[44:45], v[60:61], v[86:87], v[44:45] neg_lo:[0,0,1] neg_hi:[0,0,1]
	s_nop 0
	v_pk_add_f32 v[134:135], v[44:45], v[42:43]
	v_pk_mul_f32 v[44:45], v[50:51], v[86:87]
	v_bfe_u32 v41, v134, 16, 1
	v_pk_fma_f32 v[44:45], v[60:61], v[46:47], v[44:45]
	v_add3_u32 v41, v134, v41, s29
	v_pk_add_f32 v[46:47], v[44:45], v[42:43] op_sel:[0,1] op_sel_hi:[1,0]
	ds_write_b16_d16_hi v88, v41 offset:6800
	v_bfe_u32 v41, v46, 16, 1
	v_add3_u32 v41, v46, v41, s29
	ds_write_b16_d16_hi v88, v41 offset:6928
	ds_read_b128 v[42:45], v40 offset:1728
	ds_read_b128 v[122:125], v40 offset:1744
	ds_read_b128 v[126:129], v40 offset:1760
	ds_read_b128 v[130:133], v40 offset:1776
	s_waitcnt lgkmcnt(9)
	v_pk_fma_f32 v[86:87], v[200:201], v[64:65], 0 op_sel_hi:[0,1,0]
	v_pk_fma_f32 v[200:201], v[200:201], v[12:13], 0 op_sel:[1,0,0] op_sel_hi:[1,1,0]
	v_pk_fma_f32 v[86:87], v[202:203], v[66:67], v[86:87] op_sel_hi:[0,1,1]
	v_mov_b32_e32 v202, v203
	v_pk_fma_f32 v[200:201], v[202:203], v[14:15], v[200:201] op_sel_hi:[0,1,1]
	s_waitcnt lgkmcnt(8)
; #define LAS __attribute__((address_space(3)))
; __device__ __forceinline__ unsigned f2bf(float f) { unsigned u = __builtin_bit_cast(unsigned, f); return (u + 0x7fffu + ((u >> 16) & 1u)) >> 16; }
; __device__ __forceinline__ void s5_phase(LAS unsigned char* lds, const unsigned char* ws, const bf16_t* proj, const float* c_re, const float* c_im, const float* dskip, bf16_t* z,
;                                          int vcu, int G, int wave, int lane) {
;     ...
;             for (int k = 0; k < 32; ++k) {
;                 f32x2 xa = (f32x2){0.f, 0.f}, xb = (f32x2){0.f, 0.f};
; #pragma unroll
;                 for (int q = 0; q < 4; ++q) { const f32x4 u4 = *(const LAS f32x4*)(Uc + k * 16 + 4 * q);
;                     xa = __builtin_elementwise_fma((f32x2){u4[0], u4[0]}, (f32x2){bbre[4 * q], bbim[4 * q]}, xa);
;                     xb = __builtin_elementwise_fma((f32x2){u4[1], u4[1]}, (f32x2){bbre[4 * q + 1], bbim[4 * q + 1]}, xb);
;                     xa = __builtin_elementwise_fma((f32x2){u4[2], u4[2]}, (f32x2){bbre[4 * q + 2], bbim[4 * q + 2]}, xa);
;                     xb = __builtin_elementwise_fma((f32x2){u4[3], u4[3]}, (f32x2){bbre[4 * q + 3], bbim[4 * q + 3]}, xb); }
;                 const f32x2 xx = xa + xb;
;                 const float nr = are * hre - aim * him + xx[0], ni = are * him + aim * hre + xx[1]; hre = nr; him = ni;
;                 Hc[k * 136 + n] = (bf16_t)f2bf(hre); Hc[k * 136 + 64 + n] = (bf16_t)f2bf(him);
;             }
	v_pk_fma_f32 v[202:203], v[204:205], v[68:69], v[86:87] op_sel_hi:[0,1,1]
	v_pk_fma_f32 v[200:201], v[204:205], v[8:9], v[200:201] op_sel:[1,0,0]
	v_mov_b32_e32 v86, v207
	v_pk_fma_f32 v[202:203], v[206:207], v[70:71], v[202:203] op_sel_hi:[0,1,1]
	v_pk_fma_f32 v[200:201], v[86:87], v[10:11], v[200:201] op_sel_hi:[0,1,1]
	s_waitcnt lgkmcnt(7)
	v_pk_fma_f32 v[202:203], v[208:209], v[72:73], v[202:203] op_sel_hi:[0,1,1]
	v_pk_fma_f32 v[200:201], v[208:209], v[4:5], v[200:201] op_sel:[1,0,0]
	v_mov_b32_e32 v86, v211
	v_pk_fma_f32 v[202:203], v[210:211], v[74:75], v[202:203] op_sel_hi:[0,1,1]
	v_pk_fma_f32 v[200:201], v[86:87], v[6:7], v[200:201] op_sel_hi:[0,1,1]
	s_waitcnt lgkmcnt(6)
	v_pk_fma_f32 v[202:203], v[212:213], v[76:77], v[202:203] op_sel_hi:[0,1,1]
	v_pk_fma_f32 v[200:201], v[212:213], v[0:1], v[200:201] op_sel:[1,0,0]
	v_mov_b32_e32 v86, v215
	v_pk_fma_f32 v[202:203], v[214:215], v[78:79], v[202:203] op_sel_hi:[0,1,1]
	v_pk_fma_f32 v[200:201], v[86:87], v[2:3], v[200:201] op_sel_hi:[0,1,1]
	v_pk_add_f32 v[200:201], v[200:201], v[202:203]
	v_pk_mul_f32 v[202:203], v[50:51], v[46:47]
	s_nop 0
	v_pk_fma_f32 v[202:203], v[60:61], v[134:135], v[202:203] neg_lo:[0,0,1] neg_hi:[0,0,1]
	s_nop 0
	v_pk_add_f32 v[86:87], v[202:203], v[200:201]
	v_pk_mul_f32 v[202:203], v[50:51], v[134:135]
	v_bfe_u32 v41, v86, 16, 1
	v_pk_fma_f32 v[202:203], v[60:61], v[46:47], v[202:203]
	v_add3_u32 v41, v86, v41, s29
	v_pk_add_f32 v[46:47], v[202:203], v[200:201] op_sel:[0,1] op_sel_hi:[1,0]
	ds_write_b16_d16_hi v88, v41 offset:7072
	v_bfe_u32 v41, v46, 16, 1
	v_add3_u32 v41, v46, v41, s29
	ds_write_b16_d16_hi v88, v41 offset:7200
	ds_read_b128 v[200:203], v40 offset:1792
	ds_read_b128 v[204:207], v40 offset:1808
	ds_read_b128 v[208:211], v40 offset:1824
	ds_read_b128 v[212:215], v40 offset:1840
	s_waitcnt lgkmcnt(9)
	v_pk_fma_f32 v[134:135], v[42:43], v[64:65], 0 op_sel_hi:[0,1,0]
	v_pk_fma_f32 v[42:43], v[42:43], v[12:13], 0 op_sel:[1,0,0] op_sel_hi:[1,1,0]
	v_pk_fma_f32 v[134:135], v[44:45], v[66:67], v[134:135] op_sel_hi:[0,1,1]
	v_mov_b32_e32 v44, v45
	v_pk_fma_f32 v[42:43], v[44:45], v[14:15], v[42:43] op_sel_hi:[0,1,1]
	s_waitcnt lgkmcnt(8)
	v_pk_fma_f32 v[44:45], v[122:123], v[68:69], v[134:135] op_sel_hi:[0,1,1]
	v_pk_fma_f32 v[42:43], v[122:123], v[8:9], v[42:43] op_sel:[1,0,0]
	v_mov_b32_e32 v122, v125
	v_pk_fma_f32 v[44:45], v[124:125], v[70:71], v[44:45] op_sel_hi:[0,1,1]
	v_pk_fma_f32 v[42:43], v[122:123], v[10:11], v[42:43] op_sel_hi:[0,1,1]
	s_waitcnt lgkmcnt(7)
	v_pk_fma_f32 v[44:45], v[126:127], v[72:73], v[44:45] op_sel_hi:[0,1,1]
	v_pk_fma_f32 v[42:43], v[126:127], v[4:5], v[42:43] op_sel:[1,0,0]
	v_mov_b32_e32 v122, v129
	v_pk_fma_f32 v[44:45], v[128:129], v[74:75], v[44:45] op_sel_hi:[0,1,1]
	v_pk_fma_f32 v[42:43], v[122:123], v[6:7], v[42:43] op_sel_hi:[0,1,1]
	s_waitcnt lgkmcnt(6)
	v_pk_fma_f32 v[44:45], v[130:131], v[76:77], v[44:45] op_sel_hi:[0,1,1]
	v_pk_fma_f32 v[42:43], v[130:131], v[0:1], v[42:43] op_sel:[1,0,0]
	v_mov_b32_e32 v122, v133
	v_pk_fma_f32 v[44:45], v[132:133], v[78:79], v[44:45] op_sel_hi:[0,1,1]
	v_pk_fma_f32 v[42:43], v[122:123], v[2:3], v[42:43] op_sel_hi:[0,1,1]
	v_pk_add_f32 v[42:43], v[42:43], v[44:45]
	v_pk_mul_f32 v[44:45], v[50:51], v[46:47]
	s_nop 0
	v_pk_fma_f32 v[44:45], v[60:61], v[86:87], v[44:45] neg_lo:[0,0,1] neg_hi:[0,0,1]
	s_nop 0
	v_pk_add_f32 v[134:135], v[44:45], v[42:43]
	v_pk_mul_f32 v[44:45], v[50:51], v[86:87]
	v_bfe_u32 v41, v134, 16, 1
	v_pk_fma_f32 v[44:45], v[60:61], v[46:47], v[44:45]
	v_add3_u32 v41, v134, v41, s29
	v_pk_add_f32 v[46:47], v[44:45], v[42:43] op_sel:[0,1] op_sel_hi:[1,0]
	ds_write_b16_d16_hi v88, v41 offset:7344
	v_bfe_u32 v41, v46, 16, 1
	v_add3_u32 v41, v46, v41, s29
	ds_write_b16_d16_hi v88, v41 offset:7472
	ds_read_b128 v[42:45], v40 offset:1856
	ds_read_b128 v[122:125], v40 offset:1872
	ds_read_b128 v[126:129], v40 offset:1888
	ds_read_b128 v[130:133], v40 offset:1904
	s_waitcnt lgkmcnt(9)
	v_pk_fma_f32 v[86:87], v[200:201], v[64:65], 0 op_sel_hi:[0,1,0]
	v_pk_fma_f32 v[200:201], v[200:201], v[12:13], 0 op_sel:[1,0,0] op_sel_hi:[1,1,0]
	v_pk_fma_f32 v[86:87], v[202:203], v[66:67], v[86:87] op_sel_hi:[0,1,1]
	v_mov_b32_e32 v202, v203
	v_pk_fma_f32 v[200:201], v[202:203], v[14:15], v[200:201] op_sel_hi:[0,1,1]
	s_waitcnt lgkmcnt(8)
	v_pk_fma_f32 v[202:203], v[204:205], v[68:69], v[86:87] op_sel_hi:[0,1,1]
	v_pk_fma_f32 v[200:201], v[204:205], v[8:9], v[200:201] op_sel:[1,0,0]
	v_mov_b32_e32 v86, v207
	v_pk_fma_f32 v[202:203], v[206:207], v[70:71], v[202:203] op_sel_hi:[0,1,1]
	v_pk_fma_f32 v[200:201], v[86:87], v[10:11], v[200:201] op_sel_hi:[0,1,1]
	s_waitcnt lgkmcnt(7)
	v_pk_fma_f32 v[202:203], v[208:209], v[72:73], v[202:203] op_sel_hi:[0,1,1]
	v_pk_fma_f32 v[200:201], v[208:209], v[4:5], v[200:201] op_sel:[1,0,0]
	v_mov_b32_e32 v86, v211
	v_pk_fma_f32 v[202:203], v[210:211], v[74:75], v[202:203] op_sel_hi:[0,1,1]
	v_pk_fma_f32 v[200:201], v[86:87], v[6:7], v[200:201] op_sel_hi:[0,1,1]
	s_waitcnt lgkmcnt(6)
	v_pk_fma_f32 v[202:203], v[212:213], v[76:77], v[202:203] op_sel_hi:[0,1,1]
	v_pk_fma_f32 v[200:201], v[212:213], v[0:1], v[200:201] op_sel:[1,0,0]
	v_mov_b32_e32 v86, v215
	v_pk_fma_f32 v[202:203], v[214:215], v[78:79], v[202:203] op_sel_hi:[0,1,1]
	v_pk_fma_f32 v[200:201], v[86:87], v[2:3], v[200:201] op_sel_hi:[0,1,1]
	v_pk_add_f32 v[200:201], v[200:201], v[202:203]
	v_pk_mul_f32 v[202:203], v[50:51], v[46:47]
	s_nop 0
	v_pk_fma_f32 v[202:203], v[60:61], v[134:135], v[202:203] neg_lo:[0,0,1] neg_hi:[0,0,1]
	s_nop 0
	v_pk_add_f32 v[86:87], v[202:203], v[200:201]
	v_pk_mul_f32 v[202:203], v[50:51], v[134:135]
	v_bfe_u32 v41, v86, 16, 1
	v_pk_fma_f32 v[202:203], v[60:61], v[46:47], v[202:203]
	v_add3_u32 v41, v86, v41, s29
	v_pk_add_f32 v[46:47], v[202:203], v[200:201] op_sel:[0,1] op_sel_hi:[1,0]
	ds_write_b16_d16_hi v88, v41 offset:7616
	v_bfe_u32 v41, v46, 16, 1
	v_add3_u32 v41, v46, v41, s29
	ds_write_b16_d16_hi v88, v41 offset:7744
	ds_read_b128 v[200:203], v40 offset:1920
	ds_read_b128 v[204:207], v40 offset:1936
	ds_read_b128 v[208:211], v40 offset:1952
	ds_read_b128 v[212:215], v40 offset:1968
	s_waitcnt lgkmcnt(9)
; #define LAS __attribute__((address_space(3)))
; __device__ __forceinline__ unsigned f2bf(float f) { unsigned u = __builtin_bit_cast(unsigned, f); return (u + 0x7fffu + ((u >> 16) & 1u)) >> 16; }
; __device__ __forceinline__ void s5_phase(LAS unsigned char* lds, const unsigned char* ws, const bf16_t* proj, const float* c_re, const float* c_im, const float* dskip, bf16_t* z,
;                                          int vcu, int G, int wave, int lane) {
;     ...
;             for (int k = 0; k < 32; ++k) {
;                 f32x2 xa = (f32x2){0.f, 0.f}, xb = (f32x2){0.f, 0.f};
; #pragma unroll
;                 for (int q = 0; q < 4; ++q) { const f32x4 u4 = *(const LAS f32x4*)(Uc + k * 16 + 4 * q);
;                     xa = __builtin_elementwise_fma((f32x2){u4[0], u4[0]}, (f32x2){bbre[4 * q], bbim[4 * q]}, xa);
;                     xb = __builtin_elementwise_fma((f32x2){u4[1], u4[1]}, (f32x2){bbre[4 * q + 1], bbim[4 * q + 1]}, xb);
;                     xa = __builtin_elementwise_fma((f32x2){u4[2], u4[2]}, (f32x2){bbre[4 * q + 2], bbim[4 * q + 2]}, xa);
;                     xb = __builtin_elementwise_fma((f32x2){u4[3], u4[3]}, (f32x2){bbre[4 * q + 3], bbim[4 * q + 3]}, xb); }
;                 const f32x2 xx = xa + xb;
;                 const float nr = are * hre - aim * him + xx[0], ni = are * him + aim * hre + xx[1]; hre = nr; him = ni;
;                 Hc[k * 136 + n] = (bf16_t)f2bf(hre); Hc[k * 136 + 64 + n] = (bf16_t)f2bf(him);
;             }
; #pragma unroll
;             for (int sb = 0; sb < 2; ++sb) {
;                 f32x4 y = (f32x4){0.f, 0.f, 0.f, 0.f};
; #pragma unroll
;                 for (int ks = 0; ks < 4; ++ks) { const bf16x8 hf = *(const LAS bf16x8*)(Hc + (16 * sb + fr) * 136 + 32 * ks + 8 * fq); y = __builtin_amdgcn_mfma_f32_16x16x32_bf16(hf, cf[ks], y, 0, 0, 0); }
	v_pk_fma_f32 v[134:135], v[42:43], v[64:65], 0 op_sel_hi:[0,1,0]
	v_pk_fma_f32 v[42:43], v[42:43], v[12:13], 0 op_sel:[1,0,0] op_sel_hi:[1,1,0]
	v_pk_fma_f32 v[134:135], v[44:45], v[66:67], v[134:135] op_sel_hi:[0,1,1]
	v_mov_b32_e32 v44, v45
	v_pk_fma_f32 v[42:43], v[44:45], v[14:15], v[42:43] op_sel_hi:[0,1,1]
	s_waitcnt lgkmcnt(8)
	v_pk_fma_f32 v[44:45], v[122:123], v[68:69], v[134:135] op_sel_hi:[0,1,1]
	v_pk_fma_f32 v[42:43], v[122:123], v[8:9], v[42:43] op_sel:[1,0,0]
	v_mov_b32_e32 v122, v125
	v_pk_fma_f32 v[44:45], v[124:125], v[70:71], v[44:45] op_sel_hi:[0,1,1]
	v_pk_fma_f32 v[42:43], v[122:123], v[10:11], v[42:43] op_sel_hi:[0,1,1]
	s_waitcnt lgkmcnt(7)
	v_pk_fma_f32 v[44:45], v[126:127], v[72:73], v[44:45] op_sel_hi:[0,1,1]
	v_pk_fma_f32 v[42:43], v[126:127], v[4:5], v[42:43] op_sel:[1,0,0]
	v_mov_b32_e32 v122, v129
	v_pk_fma_f32 v[44:45], v[128:129], v[74:75], v[44:45] op_sel_hi:[0,1,1]
	v_pk_fma_f32 v[42:43], v[122:123], v[6:7], v[42:43] op_sel_hi:[0,1,1]
	s_waitcnt lgkmcnt(6)
	v_pk_fma_f32 v[44:45], v[130:131], v[76:77], v[44:45] op_sel_hi:[0,1,1]
	v_pk_fma_f32 v[42:43], v[130:131], v[0:1], v[42:43] op_sel:[1,0,0]
	v_mov_b32_e32 v122, v133
	v_pk_fma_f32 v[44:45], v[132:133], v[78:79], v[44:45] op_sel_hi:[0,1,1]
	v_pk_fma_f32 v[42:43], v[122:123], v[2:3], v[42:43] op_sel_hi:[0,1,1]
	v_pk_add_f32 v[42:43], v[42:43], v[44:45]
	v_pk_mul_f32 v[44:45], v[50:51], v[46:47]
	s_nop 0
	v_pk_fma_f32 v[44:45], v[60:61], v[86:87], v[44:45] neg_lo:[0,0,1] neg_hi:[0,0,1]
	s_nop 0
	v_pk_add_f32 v[134:135], v[44:45], v[42:43]
	v_pk_mul_f32 v[44:45], v[50:51], v[86:87]
	v_bfe_u32 v41, v134, 16, 1
	v_pk_fma_f32 v[44:45], v[60:61], v[46:47], v[44:45]
	v_add3_u32 v41, v134, v41, s29
	v_pk_add_f32 v[46:47], v[44:45], v[42:43] op_sel:[0,1] op_sel_hi:[1,0]
	ds_write_b16_d16_hi v88, v41 offset:7888
	v_bfe_u32 v41, v46, 16, 1
	v_add3_u32 v41, v46, v41, s29
	ds_write_b16_d16_hi v88, v41 offset:8016
	ds_read_b128 v[42:45], v40 offset:1984
	ds_read_b128 v[122:125], v40 offset:2000
	ds_read_b128 v[126:129], v40 offset:2016
	ds_read_b128 v[130:133], v40 offset:2032
	s_waitcnt lgkmcnt(9)
	v_pk_fma_f32 v[86:87], v[200:201], v[64:65], 0 op_sel_hi:[0,1,0]
	v_pk_fma_f32 v[200:201], v[200:201], v[12:13], 0 op_sel:[1,0,0] op_sel_hi:[1,1,0]
	v_pk_fma_f32 v[86:87], v[202:203], v[66:67], v[86:87] op_sel_hi:[0,1,1]
	v_mov_b32_e32 v202, v203
	v_pk_fma_f32 v[200:201], v[202:203], v[14:15], v[200:201] op_sel_hi:[0,1,1]
	s_waitcnt lgkmcnt(8)
	v_pk_fma_f32 v[202:203], v[204:205], v[68:69], v[86:87] op_sel_hi:[0,1,1]
	v_pk_fma_f32 v[200:201], v[204:205], v[8:9], v[200:201] op_sel:[1,0,0]
	v_mov_b32_e32 v86, v207
	v_pk_fma_f32 v[202:203], v[206:207], v[70:71], v[202:203] op_sel_hi:[0,1,1]
	v_pk_fma_f32 v[200:201], v[86:87], v[10:11], v[200:201] op_sel_hi:[0,1,1]
	s_waitcnt lgkmcnt(7)
	v_pk_fma_f32 v[202:203], v[208:209], v[72:73], v[202:203] op_sel_hi:[0,1,1]
	v_pk_fma_f32 v[200:201], v[208:209], v[4:5], v[200:201] op_sel:[1,0,0]
	v_mov_b32_e32 v86, v211
	v_pk_fma_f32 v[202:203], v[210:211], v[74:75], v[202:203] op_sel_hi:[0,1,1]
	v_pk_fma_f32 v[200:201], v[86:87], v[6:7], v[200:201] op_sel_hi:[0,1,1]
	s_waitcnt lgkmcnt(6)
	v_pk_fma_f32 v[202:203], v[212:213], v[76:77], v[202:203] op_sel_hi:[0,1,1]
	v_pk_fma_f32 v[200:201], v[212:213], v[0:1], v[200:201] op_sel:[1,0,0]
	v_mov_b32_e32 v86, v215
	v_pk_fma_f32 v[202:203], v[214:215], v[78:79], v[202:203] op_sel_hi:[0,1,1]
	v_pk_fma_f32 v[200:201], v[86:87], v[2:3], v[200:201] op_sel_hi:[0,1,1]
	v_pk_add_f32 v[200:201], v[200:201], v[202:203]
	v_pk_mul_f32 v[202:203], v[50:51], v[46:47]
	s_nop 0
	v_pk_fma_f32 v[202:203], v[60:61], v[134:135], v[202:203] neg_lo:[0,0,1] neg_hi:[0,0,1]
	s_nop 0
	v_pk_add_f32 v[86:87], v[202:203], v[200:201]
	v_pk_mul_f32 v[202:203], v[50:51], v[134:135]
	v_bfe_u32 v41, v86, 16, 1
	v_pk_fma_f32 v[202:203], v[60:61], v[46:47], v[202:203]
	v_add3_u32 v41, v86, v41, s29
	v_pk_add_f32 v[46:47], v[202:203], v[200:201] op_sel:[0,1] op_sel_hi:[1,0]
	ds_write_b16_d16_hi v88, v41 offset:8160
	v_bfe_u32 v41, v46, 16, 1
	v_add3_u32 v41, v46, v41, s29
	ds_write_b16_d16_hi v88, v41 offset:8288
	s_waitcnt lgkmcnt(5)
	v_pk_fma_f32 v[40:41], v[42:43], v[64:65], 0 op_sel_hi:[0,1,0]
	v_pk_fma_f32 v[42:43], v[42:43], v[12:13], 0 op_sel:[1,0,0] op_sel_hi:[1,1,0]
	v_pk_fma_f32 v[40:41], v[44:45], v[66:67], v[40:41] op_sel_hi:[0,1,1]
	v_mov_b32_e32 v44, v45
	v_pk_fma_f32 v[42:43], v[44:45], v[14:15], v[42:43] op_sel_hi:[0,1,1]
	s_waitcnt lgkmcnt(4)
	v_pk_fma_f32 v[40:41], v[122:123], v[68:69], v[40:41] op_sel_hi:[0,1,1]
	v_pk_fma_f32 v[42:43], v[122:123], v[8:9], v[42:43] op_sel:[1,0,0]
	v_mov_b32_e32 v44, v125
	v_pk_fma_f32 v[40:41], v[124:125], v[70:71], v[40:41] op_sel_hi:[0,1,1]
	v_pk_fma_f32 v[42:43], v[44:45], v[10:11], v[42:43] op_sel_hi:[0,1,1]
	s_waitcnt lgkmcnt(3)
	v_pk_fma_f32 v[40:41], v[126:127], v[72:73], v[40:41] op_sel_hi:[0,1,1]
	v_pk_fma_f32 v[42:43], v[126:127], v[4:5], v[42:43] op_sel:[1,0,0]
	v_mov_b32_e32 v44, v129
	v_pk_fma_f32 v[40:41], v[128:129], v[74:75], v[40:41] op_sel_hi:[0,1,1]
	v_pk_fma_f32 v[42:43], v[44:45], v[6:7], v[42:43] op_sel_hi:[0,1,1]
	s_waitcnt lgkmcnt(2)
	v_pk_fma_f32 v[40:41], v[130:131], v[76:77], v[40:41] op_sel_hi:[0,1,1]
	v_pk_fma_f32 v[42:43], v[130:131], v[0:1], v[42:43] op_sel:[1,0,0]
	v_mov_b32_e32 v44, v133
	v_pk_fma_f32 v[40:41], v[132:133], v[78:79], v[40:41] op_sel_hi:[0,1,1]
	v_pk_fma_f32 v[42:43], v[44:45], v[2:3], v[42:43] op_sel_hi:[0,1,1]
	v_pk_add_f32 v[40:41], v[42:43], v[40:41]
	v_pk_mul_f32 v[42:43], v[80:81], v[46:47] op_sel_hi:[1,0]
	v_lshl_add_u64 v[130:131], v[82:83], 0, s[26:27]
	v_pk_fma_f32 v[44:45], v[60:61], v[86:87], v[42:43] neg_lo:[0,0,1] neg_hi:[0,0,1]
	v_pk_fma_f32 v[42:43], v[60:61], v[86:87], v[42:43] op_sel_hi:[1,0,1]
	s_nop 0
	v_mov_b32_e32 v45, v43
	v_pk_add_f32 v[86:87], v[44:45], v[40:41]
	s_nop 0
	v_bfe_u32 v40, v86, 16, 1
	v_add3_u32 v40, v86, v40, s29
	ds_write_b16_d16_hi v88, v40 offset:8432
	v_bfe_u32 v40, v87, 16, 1
	v_add3_u32 v40, v87, v40, s29
	ds_write_b16_d16_hi v88, v40 offset:8560
	ds_read_b128 v[40:43], v102
	ds_read_b128 v[44:47], v102 offset:64
	s_waitcnt lgkmcnt(1)
; #define LAS __attribute__((address_space(3)))
; __device__ __forceinline__ unsigned f2bf(float f) { unsigned u = __builtin_bit_cast(unsigned, f); return (u + 0x7fffu + ((u >> 16) & 1u)) >> 16; }
; __device__ __forceinline__ float gelu_tanh_f(float y) { return y * fast_sigmoid(1.5957691216057308f * (y + 0.044715f * y * y * y)); }
; __device__ __forceinline__ void s5_phase(LAS unsigned char* lds, const unsigned char* ws, const bf16_t* proj, const float* c_re, const float* c_im, const float* dskip, bf16_t* z,
;                                          int vcu, int G, int wave, int lane) {
;     ...
; #pragma unroll
;             for (int sb = 0; sb < 2; ++sb) {
;                 f32x4 y = (f32x4){0.f, 0.f, 0.f, 0.f};
; #pragma unroll
;                 for (int ks = 0; ks < 4; ++ks) { const bf16x8 hf = *(const LAS bf16x8*)(Hc + (16 * sb + fr) * 136 + 32 * ks + 8 * fq); y = __builtin_amdgcn_mfma_f32_16x16x32_bf16(hf, cf[ks], y, 0, 0, 0); }
; #pragma unroll
;                 for (int i = 0; i < 4; ++i) { const size_t row = row0 + 16 * sb + 4 * fq + i;
;                     const float yy = y[i] + dsk * bf2f(uu[sb][i]);
;                     z[row * 1024 + g * 16 + fr] = (bf16_t)f2bf(gelu_tanh_f(yy)); }
;             }
;             ua = ua_n; ub = ub_n;
; #pragma unroll
;             for (int sb = 0; sb < 2; ++sb)
; #pragma unroll
;                 for (int i = 0; i < 4; ++i) uu[sb][i] = uu_n[sb][i];
	v_mfma_f32_16x16x32_bf16 v[40:43], v[40:43], v[16:19], 0
	ds_read_b128 v[122:125], v102 offset:128
	ds_read_b128 v[126:129], v102 offset:4544
	s_waitcnt lgkmcnt(2)
	v_mfma_f32_16x16x32_bf16 v[40:43], v[44:47], v[20:23], v[40:43]
	ds_read_b128 v[44:47], v102 offset:192
	s_waitcnt lgkmcnt(2)
	v_mfma_f32_16x16x32_bf16 v[40:43], v[122:125], v[24:27], v[40:43]
	ds_read_b128 v[122:125], v102 offset:4480
	s_waitcnt lgkmcnt(1)
	v_mfma_f32_16x16x32_bf16 v[40:43], v[44:47], v[28:31], v[40:43]
	v_lshlrev_b32_e32 v44, 16, v120
	s_nop 6
	v_fma_f32 v40, v104, v44, v40
	v_mul_f32_e32 v44, 0x3d372713, v40
	v_mul_f32_e32 v44, v40, v44
	v_fma_f32 v44, v40, v44, v40
	v_mul_f32_e32 v44, 0x3fcc422a, v44
	v_mul_f32_e32 v44, 0xbfb8aa3b, v44
	v_exp_f32_e32 v44, v44
	s_nop 0
	v_add_f32_e32 v44, 1.0, v44
	v_rcp_f32_e32 v44, v44
	s_nop 0
	v_mul_f32_e32 v40, v40, v44
	v_bfe_u32 v44, v40, 16, 1
	v_add3_u32 v46, v40, v44, s29
	v_lshlrev_b32_e32 v40, 16, v119
	v_fma_f32 v47, v104, v40, v41
	v_mul_f32_e32 v40, 0x3d372713, v47
	v_mul_f32_e32 v40, v47, v40
	v_fma_f32 v40, v47, v40, v47
	v_mul_f32_e32 v40, 0x3fcc422a, v40
	v_mul_f32_e32 v40, 0xbfb8aa3b, v40
	v_lshl_add_u64 v[44:45], v[84:85], 0, s[26:27]
	v_exp_f32_e32 v119, v40
	v_add_co_u32_e64 v40, s[0:1], s31, v44
	s_add_u32 s26, s26, 0x10000
	s_nop 0
	v_addc_co_u32_e64 v41, s[0:1], 0, v45, s[0:1]
	v_add_co_u32_e64 v132, s[0:1], s33, v44
	v_add_f32_e32 v119, 1.0, v119
	s_nop 0
	v_addc_co_u32_e64 v133, s[0:1], 0, v45, s[0:1]
	v_rcp_f32_e32 v119, v119
	global_store_short_d16_hi v[132:133], v46, off offset:-4096
	v_lshlrev_b32_e32 v46, 16, v118
	v_fma_f32 v42, v104, v46, v42
	v_mul_f32_e32 v46, 0x3d372713, v42
	v_mul_f32_e32 v46, v42, v46
	v_mul_f32_e32 v44, v47, v119
	v_fma_f32 v46, v42, v46, v42
	v_bfe_u32 v45, v44, 16, 1
	v_mul_f32_e32 v46, 0x3fcc422a, v46
	v_mul_f32_e32 v46, 0xbfb8aa3b, v46
	v_add3_u32 v44, v44, v45, s29
	v_exp_f32_e32 v118, v46
	global_store_short_d16_hi v[40:41], v44, off offset:2048
	ds_read_b128 v[44:47], v102 offset:4352
	v_lshlrev_b32_e32 v41, 16, v109
	v_add_f32_e32 v40, 1.0, v118
	ds_read_b128 v[118:121], v102 offset:4416
	s_waitcnt lgkmcnt(1)
	v_mfma_f32_16x16x32_bf16 v[44:47], v[44:47], v[16:19], 0
	v_fmac_f32_e32 v43, v104, v41
	v_mul_f32_e32 v41, 0x3d372713, v43
	v_mul_f32_e32 v41, v43, v41
	s_waitcnt lgkmcnt(0)
	v_mfma_f32_16x16x32_bf16 v[44:47], v[118:121], v[20:23], v[44:47]
	v_fma_f32 v41, v43, v41, v43
	v_mul_f32_e32 v41, 0x3fcc422a, v41
	v_mul_f32_e32 v41, 0xbfb8aa3b, v41
	v_mfma_f32_16x16x32_bf16 v[44:47], v[122:125], v[24:27], v[44:47]
	v_exp_f32_e32 v41, v41
	v_rcp_f32_e32 v40, v40
	s_addc_u32 s27, s27, 0
	v_mfma_f32_16x16x32_bf16 v[44:47], v[126:129], v[28:31], v[44:47]
	v_add_f32_e32 v41, 1.0, v41
	v_rcp_f32_e32 v41, v41
	v_mul_f32_e32 v40, v42, v40
	v_bfe_u32 v42, v40, 16, 1
	v_add3_u32 v40, v40, v42, s29
	s_nop 2
	v_fma_f32 v44, v104, v108, v44
	v_mul_f32_e32 v108, 0x3d372713, v44
	v_mul_f32_e32 v108, v44, v108
	v_fma_f32 v108, v44, v108, v44
	v_mul_f32_e32 v108, 0x3fcc422a, v108
	v_mul_f32_e32 v108, 0xbfb8aa3b, v108
	v_exp_f32_e32 v108, v108
	global_store_short_d16_hi v[132:133], v40, off
	v_mul_f32_e32 v40, v43, v41
	v_bfe_u32 v42, v40, 16, 1
	v_add_f32_e32 v41, 1.0, v108
	v_rcp_f32_e32 v41, v41
	v_add3_u32 v40, v40, v42, s29
	global_store_short_d16_hi v[132:133], v40, off offset:2048
	s_add_i32 s34, s34, 0x28000
	v_mul_f32_e32 v40, v44, v41
	s_waitcnt vmcnt(16)
	v_lshlrev_b32_e32 v41, 16, v107
	v_fma_f32 v42, v104, v41, v45
	v_mul_f32_e32 v41, 0x3d372713, v42
	v_mul_f32_e32 v41, v42, v41
	v_fma_f32 v41, v42, v41, v42
	v_mul_f32_e32 v41, 0x3fcc422a, v41
	v_mul_f32_e32 v41, 0xbfb8aa3b, v41
	v_exp_f32_e32 v41, v41
	v_bfe_u32 v43, v40, 16, 1
	v_add3_u32 v43, v40, v43, s29
	v_or_b32_e32 v40, 0x8000, v130
	v_add_f32_e32 v41, 1.0, v41
	v_rcp_f32_e32 v44, v41
	v_mov_b32_e32 v41, v131
	v_lshl_add_u64 v[40:41], v[62:63], 0, v[40:41]
	global_store_short_d16_hi v[40:41], v43, off
	s_waitcnt vmcnt(16)
	v_lshlrev_b32_e32 v41, 16, v106
	v_mul_f32_e32 v40, v42, v44
	v_fma_f32 v42, v104, v41, v46
	v_mul_f32_e32 v41, 0x3d372713, v42
	v_mul_f32_e32 v41, v42, v41
	v_fma_f32 v41, v42, v41, v42
	v_mul_f32_e32 v41, 0x3fcc422a, v41
	v_mul_f32_e32 v41, 0xbfb8aa3b, v41
	v_exp_f32_e32 v41, v41
	v_bfe_u32 v43, v40, 16, 1
	v_add3_u32 v43, v40, v43, s29
	v_or_b32_e32 v40, 0x8800, v130
	v_add_f32_e32 v41, 1.0, v41
	v_rcp_f32_e32 v44, v41
	v_mov_b32_e32 v41, v131
	v_lshl_add_u64 v[40:41], v[62:63], 0, v[40:41]
	global_store_short_d16_hi v[40:41], v43, off
	s_waitcnt vmcnt(16)
	v_lshlrev_b32_e32 v41, 16, v105
	v_fmac_f32_e32 v47, v104, v41
	v_mul_f32_e32 v41, 0x3d372713, v47
	v_mul_f32_e32 v41, v47, v41
	v_fma_f32 v41, v47, v41, v47
	v_mul_f32_e32 v41, 0x3fcc422a, v41
	v_mul_f32_e32 v41, 0xbfb8aa3b, v41
	v_exp_f32_e32 v41, v41
	v_mul_f32_e32 v40, v42, v44
	v_bfe_u32 v42, v40, 16, 1
	v_add3_u32 v42, v40, v42, s29
	v_add_f32_e32 v41, 1.0, v41
	v_rcp_f32_e32 v43, v41
	v_or_b32_e32 v40, 0x9000, v130
	v_mov_b32_e32 v41, v131
	v_lshl_add_u64 v[40:41], v[62:63], 0, v[40:41]
	global_store_short_d16_hi v[40:41], v42, off
	v_mul_f32_e32 v40, v47, v43
	v_bfe_u32 v41, v40, 16, 1
	v_or_b32_e32 v130, 0x9800, v130
	v_add3_u32 v42, v40, v41, s29
	v_lshl_add_u64 v[40:41], v[62:63], 0, v[130:131]
	global_store_short_d16_hi v[40:41], v42, off
	s_waitcnt vmcnt(16)
	v_mov_b64_e32 v[46:47], v[38:39]
	v_mov_b64_e32 v[42:43], v[34:35]
	s_cmp_eq_u32 s26, 0x400000
	s_waitcnt vmcnt(13)
	v_mov_b32_e32 v118, v117
	v_mov_b32_e32 v119, v111
	v_mov_b32_e32 v120, v110
	s_waitcnt vmcnt(12)
	v_mov_b32_e32 v109, v112
	s_waitcnt vmcnt(11)
	v_mov_b32_e32 v108, v113
	s_waitcnt vmcnt(10)
	v_mov_b32_e32 v107, v114
	s_waitcnt vmcnt(9)
	v_mov_b32_e32 v106, v115
	s_waitcnt vmcnt(8)
	v_mov_b32_e32 v105, v116
	v_mov_b64_e32 v[44:45], v[36:37]
	v_mov_b64_e32 v[40:41], v[32:33]
	s_cbranch_scc1 .LBB0_384
